# all-DMA GEMMs + LDS top reads reordered by first use (first MFMA waits for 2 reads instead of 5)
# speedup vs baseline: 1.0241x; 1.0051x over previous
.LBB0_128:
	s_setprio 1
	s_add_u32 s98, s42, s27
	s_addc_u32 s99, s43, 0
	s_add_u32 s98, s98, 0x80
	s_addc_u32 s99, s99, 0
	ds_read_b128 v[132:135], v127 offset:16384
	ds_read_b128 v[140:143], v129
	ds_read_b128 v[152:155], v127 offset:18432
	ds_read_b128 v[160:163], v127 offset:20480
	ds_read_b128 v[164:167], v127 offset:22528
	ds_read_b128 v[144:147], v129 offset:2048
	ds_read_b128 v[148:151], v129 offset:4096
	ds_read_b128 v[156:159], v129 offset:6144
	s_add_u32 m0, s100, 0x8000
	s_waitcnt lgkmcnt(6)
	v_mfma_f32_16x16x32_bf16 v[34:37], v[132:135], v[140:143], v[34:37]
	global_load_lds_dwordx4 v194, s[98:99]
	s_waitcnt lgkmcnt(5)
	v_mfma_f32_16x16x32_bf16 v[94:97], v[152:155], v[140:143], v[94:97]
	ds_read_b128 v[198:201], v128
	s_add_u32 m0, s100, 0xc000
	s_waitcnt lgkmcnt(5)
	v_mfma_f32_16x16x32_bf16 v[38:41], v[160:163], v[140:143], v[38:41]
	global_load_lds_dwordx4 v195, s[98:99]
	s_waitcnt lgkmcnt(4)
	v_mfma_f32_16x16x32_bf16 v[90:93], v[164:167], v[140:143], v[90:93]
	ds_read_b128 v[140:143], v128 offset:2048
	s_add_u32 m0, s100, 0x9000
	s_waitcnt lgkmcnt(4)
	v_mfma_f32_16x16x32_bf16 v[42:45], v[132:135], v[144:147], v[42:45]
	global_load_lds_dwordx4 v196, s[98:99]
	v_mfma_f32_16x16x32_bf16 v[86:89], v[152:155], v[144:147], v[86:89]
	ds_read_b128 v[210:213], v128 offset:4096
	s_add_u32 m0, s100, 0xd000
	v_mfma_f32_16x16x32_bf16 v[46:49], v[160:163], v[144:147], v[46:49]
	global_load_lds_dwordx4 v197, s[98:99]
	v_mfma_f32_16x16x32_bf16 v[82:85], v[164:167], v[144:147], v[82:85]
	ds_read_b128 v[144:147], v128 offset:6144
	s_add_u32 m0, s100, 0xa000
	s_waitcnt lgkmcnt(5)
	v_mfma_f32_16x16x32_bf16 v[50:53], v[132:135], v[148:151], v[50:53]
	global_load_lds_dwordx4 v202, s[98:99]
	v_mfma_f32_16x16x32_bf16 v[78:81], v[152:155], v[148:151], v[78:81]
	ds_read_b128 v[222:225], v130 offset:16384
	s_add_u32 m0, s100, 0xe000
	v_mfma_f32_16x16x32_bf16 v[54:57], v[160:163], v[148:151], v[54:57]
	global_load_lds_dwordx4 v203, s[98:99]
	v_mfma_f32_16x16x32_bf16 v[70:73], v[164:167], v[148:151], v[70:73]
	ds_read_b128 v[148:151], v130 offset:18432
	s_add_u32 m0, s100, 0xb000
	s_waitcnt lgkmcnt(6)
	v_mfma_f32_16x16x32_bf16 v[58:61], v[132:135], v[156:159], v[58:61]
	global_load_lds_dwordx4 v204, s[98:99]
	v_mfma_f32_16x16x32_bf16 v[66:69], v[152:155], v[156:159], v[66:69]
	ds_read_b128 v[152:155], v130 offset:20480
	s_add_u32 m0, s100, 0xf000
	v_mfma_f32_16x16x32_bf16 v[62:65], v[160:163], v[156:159], v[62:65]
	global_load_lds_dwordx4 v205, s[98:99]
	v_mfma_f32_16x16x32_bf16 v[74:77], v[164:167], v[156:159], v[74:77]
	ds_read_b128 v[156:159], v130 offset:22528
	s_waitcnt lgkmcnt(3)
	v_mfma_f32_16x16x32_bf16 v[34:37], v[222:225], v[198:201], v[34:37]
	s_waitcnt lgkmcnt(2)
	v_mfma_f32_16x16x32_bf16 v[94:97], v[148:151], v[198:201], v[94:97]
	s_waitcnt lgkmcnt(1)
	v_mfma_f32_16x16x32_bf16 v[38:41], v[152:155], v[198:201], v[38:41]
	s_waitcnt lgkmcnt(0)
	v_mfma_f32_16x16x32_bf16 v[90:93], v[156:159], v[198:201], v[90:93]
	v_mfma_f32_16x16x32_bf16 v[42:45], v[222:225], v[140:143], v[42:45]
	v_mfma_f32_16x16x32_bf16 v[86:89], v[148:151], v[140:143], v[86:89]
	v_mfma_f32_16x16x32_bf16 v[46:49], v[152:155], v[140:143], v[46:49]
	v_mfma_f32_16x16x32_bf16 v[82:85], v[156:159], v[140:143], v[82:85]
	v_mfma_f32_16x16x32_bf16 v[50:53], v[222:225], v[210:213], v[50:53]
	v_mfma_f32_16x16x32_bf16 v[78:81], v[148:151], v[210:213], v[78:81]
	v_mfma_f32_16x16x32_bf16 v[54:57], v[152:155], v[210:213], v[54:57]
	v_mfma_f32_16x16x32_bf16 v[70:73], v[156:159], v[210:213], v[70:73]
	v_mfma_f32_16x16x32_bf16 v[58:61], v[222:225], v[144:147], v[58:61]
	v_mfma_f32_16x16x32_bf16 v[66:69], v[148:151], v[144:147], v[66:69]
	v_mfma_f32_16x16x32_bf16 v[62:65], v[152:155], v[144:147], v[62:65]
	v_mfma_f32_16x16x32_bf16 v[74:77], v[156:159], v[144:147], v[74:77]
	s_waitcnt vmcnt(0)
	s_setprio 0
	s_waitcnt lgkmcnt(0)
	s_barrier
	s_setprio 1
	s_add_u32 s98, s98, 0x80
	s_addc_u32 s99, s99, 0
	ds_read_b128 v[26:29], v127 offset:49152
	ds_read_b128 v[10:13], v129 offset:32768
	ds_read_b128 v[30:33], v127 offset:51200
	ds_read_b128 v[148:151], v127 offset:53248
	ds_read_b128 v[152:155], v127 offset:55296
	ds_read_b128 v[18:21], v129 offset:34816
	ds_read_b128 v[140:143], v129 offset:36864
	ds_read_b128 v[144:147], v129 offset:38912
	s_add_u32 m0, s100, 0x0
	s_waitcnt lgkmcnt(6)
	v_mfma_f32_16x16x32_bf16 v[34:37], v[26:29], v[10:13], v[34:37]
	global_load_lds_dwordx4 v194, s[98:99]
	s_waitcnt lgkmcnt(5)
	v_mfma_f32_16x16x32_bf16 v[94:97], v[30:33], v[10:13], v[94:97]
	ds_read_b128 v[156:159], v128 offset:32768
	s_add_u32 m0, s100, 0x4000
	s_waitcnt lgkmcnt(5)
	v_mfma_f32_16x16x32_bf16 v[38:41], v[148:151], v[10:13], v[38:41]
	global_load_lds_dwordx4 v195, s[98:99]
	s_waitcnt lgkmcnt(4)
	v_mfma_f32_16x16x32_bf16 v[90:93], v[152:155], v[10:13], v[90:93]
	ds_read_b128 v[164:167], v128 offset:34816
	s_add_u32 m0, s100, 0x1000
	s_waitcnt lgkmcnt(4)
	v_mfma_f32_16x16x32_bf16 v[42:45], v[26:29], v[18:21], v[42:45]
	global_load_lds_dwordx4 v196, s[98:99]
	v_mfma_f32_16x16x32_bf16 v[86:89], v[30:33], v[18:21], v[86:89]
	ds_read_b128 v[198:201], v128 offset:36864
	s_add_u32 m0, s100, 0x5000
	v_mfma_f32_16x16x32_bf16 v[46:49], v[148:151], v[18:21], v[46:49]
	global_load_lds_dwordx4 v197, s[98:99]
	v_mfma_f32_16x16x32_bf16 v[82:85], v[152:155], v[18:21], v[82:85]
	ds_read_b128 v[210:213], v128 offset:38912
	s_add_u32 m0, s100, 0x2000
	s_waitcnt lgkmcnt(5)
	v_mfma_f32_16x16x32_bf16 v[50:53], v[26:29], v[140:143], v[50:53]
	global_load_lds_dwordx4 v202, s[98:99]
	v_mfma_f32_16x16x32_bf16 v[78:81], v[30:33], v[140:143], v[78:81]
	ds_read_b128 v[222:225], v130 offset:49152
	s_add_u32 m0, s100, 0x6000
	v_mfma_f32_16x16x32_bf16 v[54:57], v[148:151], v[140:143], v[54:57]
	global_load_lds_dwordx4 v203, s[98:99]
	v_mfma_f32_16x16x32_bf16 v[70:73], v[152:155], v[140:143], v[70:73]
	ds_read_b128 v[140:143], v130 offset:51200
	s_add_u32 m0, s100, 0x3000
	s_waitcnt lgkmcnt(6)
	v_mfma_f32_16x16x32_bf16 v[58:61], v[26:29], v[144:147], v[58:61]
	global_load_lds_dwordx4 v204, s[98:99]
	v_mfma_f32_16x16x32_bf16 v[66:69], v[30:33], v[144:147], v[66:69]
	ds_read_b128 v[230:233], v130 offset:53248
	s_add_u32 m0, s100, 0x7000
	v_mfma_f32_16x16x32_bf16 v[62:65], v[148:151], v[144:147], v[62:65]
	global_load_lds_dwordx4 v205, s[98:99]
	v_mfma_f32_16x16x32_bf16 v[74:77], v[152:155], v[144:147], v[74:77]
	ds_read_b128 v[144:147], v130 offset:55296
	s_waitcnt lgkmcnt(3)
	v_mfma_f32_16x16x32_bf16 v[34:37], v[222:225], v[156:159], v[34:37]
	s_waitcnt lgkmcnt(2)
	v_mfma_f32_16x16x32_bf16 v[94:97], v[140:143], v[156:159], v[94:97]
	s_waitcnt lgkmcnt(1)
	v_mfma_f32_16x16x32_bf16 v[38:41], v[230:233], v[156:159], v[38:41]
	s_waitcnt lgkmcnt(0)
	v_mfma_f32_16x16x32_bf16 v[90:93], v[144:147], v[156:159], v[90:93]
	v_mfma_f32_16x16x32_bf16 v[42:45], v[222:225], v[164:167], v[42:45]
	v_mfma_f32_16x16x32_bf16 v[86:89], v[140:143], v[164:167], v[86:89]
	v_mfma_f32_16x16x32_bf16 v[46:49], v[230:233], v[164:167], v[46:49]
	v_mfma_f32_16x16x32_bf16 v[82:85], v[144:147], v[164:167], v[82:85]
	v_mfma_f32_16x16x32_bf16 v[50:53], v[222:225], v[198:201], v[50:53]
	v_mfma_f32_16x16x32_bf16 v[78:81], v[140:143], v[198:201], v[78:81]
	v_mfma_f32_16x16x32_bf16 v[54:57], v[230:233], v[198:201], v[54:57]
	v_mfma_f32_16x16x32_bf16 v[70:73], v[144:147], v[198:201], v[70:73]
	v_mfma_f32_16x16x32_bf16 v[58:61], v[222:225], v[210:213], v[58:61]
	v_mfma_f32_16x16x32_bf16 v[66:69], v[140:143], v[210:213], v[66:69]
	v_mfma_f32_16x16x32_bf16 v[62:65], v[230:233], v[210:213], v[62:65]
	v_mfma_f32_16x16x32_bf16 v[74:77], v[144:147], v[210:213], v[74:77]
	s_waitcnt vmcnt(0)
	s_setprio 0
	s_add_i32 s8, s8, 2
	s_add_u32 s42, s42, 0x100
	s_addc_u32 s43, s43, 0
	s_cmp_lt_u32 s8, 40
	s_waitcnt lgkmcnt(0)
	s_barrier
	s_cbranch_scc1 .LBB0_128
	v_mov_b32_e32 v2, v194
	v_mov_b32_e32 v3, v195
	v_mov_b32_e32 v4, v196
	v_mov_b32_e32 v5, v197
	v_mov_b32_e32 v6, v202
	v_mov_b32_e32 v7, v203
	v_mov_b32_e32 v8, v204
	v_mov_b32_e32 v9, v205
	s_add_u32 s98, s42, s27
	s_addc_u32 s99, s43, 0
	s_add_u32 s98, s98, 0x80
	s_addc_u32 s99, s99, 0
	s_add_i32 s8, s11, s2
	s_cmpk_lt_u32 s8, 0x100
	s_cselect_b32 s10, s8, s11
	s_lshr_b32 s9, s10, 3
	s_and_b32 s9, s9, 0x1fffff8
	s_add_i32 s9, s9, s21
	s_and_b32 s11, s10, 7
	s_or_b32 s9, s9, s11
	v_mov_b32_e32 v0, v169
	s_lshl_b32 s9, s9, 7
	s_movk_i32 s11, 0xb00
	v_lshrrev_b32_e32 v98, 3, v0
	v_add_u32_e32 v98, s9, v98
	v_lshlrev_b32_e32 v0, 3, v0
	v_mul_lo_u32 v98, v98, s11
	s_lshl_b32 s10, s10, 4
	v_and_or_b32 v0, v0, 56, v98
	v_mov_b32_e32 v98, v169
	s_and_b32 s10, s10, 0x380
	s_cmpk_gt_u32 s8, 0xff
	s_cselect_b32 s101, 1, 0
	v_lshrrev_b32_e32 v99, 3, v98
	v_add_u32_e32 v99, s10, v99
	v_lshlrev_b32_e32 v98, 3, v98
	v_mul_lo_u32 v99, v99, s11
	v_and_or_b32 v164, v98, 56, v99
	v_add_u32_e32 v114, 0x16000, v0
	v_add_u32_e32 v124, 0x2c000, v0
	v_add_u32_e32 v136, 0x42000, v0
	v_add_u32_e32 v174, 0x16000, v164
	v_add_u32_e32 v176, 0x2c000, v164
	v_add_u32_e32 v178, 0x42000, v164
	s_setprio 1
	ds_read_b128 v[98:101], v127 offset:16384
	ds_read_b128 v[102:105], v129
	ds_read_b128 v[110:113], v127 offset:18432
	ds_read_b128 v[144:147], v127 offset:20480
	ds_read_b128 v[148:151], v127 offset:22528
	ds_read_b128 v[106:109], v129 offset:2048
	ds_read_b128 v[132:135], v129 offset:4096
	ds_read_b128 v[140:143], v129 offset:6144
	v_lshrrev_b32_e32 v14, 3, v169
	v_and_b32_e32 v15, 3, v14
	v_bfe_u32 v16, v14, 4, 1
	v_lshl_or_b32 v15, v16, 2, v15
	v_bfe_u32 v16, v14, 2, 1
	v_lshl_or_b32 v15, v16, 3, v15
	v_bfe_u32 v16, v14, 3, 1
	v_lshl_or_b32 v15, v16, 4, v15
	v_sub_u32_e32 v15, v15, v14
	v_mul_i32_i24_e32 v15, 0xb00, v15
	v_and_b32_e32 v14, 7, v14
	v_lshlrev_b32_e32 v14, 3, v14
	v_xor_b32_e32 v0, v0, v14
	v_add_u32_e32 v164, v164, v15
	v_xor_b32_e32 v164, v164, v14
	v_xor_b32_e32 v114, v114, v14
	v_add_u32_e32 v174, v174, v15
	v_xor_b32_e32 v174, v174, v14
	v_xor_b32_e32 v124, v124, v14
	v_add_u32_e32 v176, v176, v15
	v_xor_b32_e32 v176, v176, v14
	v_xor_b32_e32 v136, v136, v14
	v_add_u32_e32 v178, v178, v15
	v_xor_b32_e32 v178, v178, v14
	v_readlane_b32 s14, v254, 33
	v_readlane_b32 s15, v254, 34
	v_mov_b32_e32 v165, v1
	v_mov_b32_e32 v115, v1
	v_mov_b32_e32 v175, v1
	v_mov_b32_e32 v125, v1
	v_mov_b32_e32 v177, v1
	v_mov_b32_e32 v137, v1
	v_mov_b32_e32 v179, v1
	v_lshl_add_u64 v[180:181], v[0:1], 1, s[14:15]
	v_lshl_add_u64 v[186:187], v[164:165], 1, s[38:39]
	v_lshl_add_u64 v[114:115], v[114:115], 1, s[14:15]
	v_lshl_add_u64 v[174:175], v[174:175], 1, s[38:39]
	v_lshl_add_u64 v[188:189], v[124:125], 1, s[14:15]
	v_lshl_add_u64 v[176:177], v[176:177], 1, s[38:39]
	v_lshl_add_u64 v[136:137], v[136:137], 1, s[14:15]
	v_lshl_add_u64 v[178:179], v[178:179], 1, s[38:39]
	s_add_u32 m0, s100, 0x8000
	s_waitcnt lgkmcnt(6)
	v_mfma_f32_16x16x32_bf16 v[152:155], v[98:101], v[102:105], v[34:37]
	global_load_lds_dwordx4 v2, s[98:99]
	s_waitcnt lgkmcnt(5)
	v_mfma_f32_16x16x32_bf16 v[94:97], v[110:113], v[102:105], v[94:97]
	ds_read_b128 v[156:159], v128
	s_add_u32 m0, s100, 0xc000
	s_waitcnt lgkmcnt(5)
	v_mfma_f32_16x16x32_bf16 v[160:163], v[144:147], v[102:105], v[38:41]
	global_load_lds_dwordx4 v3, s[98:99]
	s_waitcnt lgkmcnt(4)
	v_mfma_f32_16x16x32_bf16 v[90:93], v[148:151], v[102:105], v[90:93]
	ds_read_b128 v[102:105], v128 offset:2048
	s_add_u32 m0, s100, 0x9000
	s_waitcnt lgkmcnt(4)
	v_mfma_f32_16x16x32_bf16 v[164:167], v[98:101], v[106:109], v[42:45]
	global_load_lds_dwordx4 v4, s[98:99]
	v_mfma_f32_16x16x32_bf16 v[86:89], v[110:113], v[106:109], v[86:89]
	ds_read_b128 v[194:197], v128 offset:4096
	s_add_u32 m0, s100, 0xd000
	v_mfma_f32_16x16x32_bf16 v[198:201], v[144:147], v[106:109], v[46:49]
	global_load_lds_dwordx4 v5, s[98:99]
	v_mfma_f32_16x16x32_bf16 v[82:85], v[148:151], v[106:109], v[82:85]
	ds_read_b128 v[106:109], v128 offset:6144
	s_add_u32 m0, s100, 0xa000
	s_waitcnt lgkmcnt(5)
	v_mfma_f32_16x16x32_bf16 v[202:205], v[98:101], v[132:135], v[50:53]
	global_load_lds_dwordx4 v6, s[98:99]
	v_mfma_f32_16x16x32_bf16 v[78:81], v[110:113], v[132:135], v[78:81]
	ds_read_b128 v[206:209], v130 offset:16384
	s_add_u32 m0, s100, 0xe000
	v_mfma_f32_16x16x32_bf16 v[210:213], v[144:147], v[132:135], v[54:57]
	global_load_lds_dwordx4 v7, s[98:99]
	v_mfma_f32_16x16x32_bf16 v[70:73], v[148:151], v[132:135], v[70:73]
	ds_read_b128 v[132:135], v130 offset:18432
	s_add_u32 m0, s100, 0xb000
	s_waitcnt lgkmcnt(6)
	v_mfma_f32_16x16x32_bf16 v[98:101], v[98:101], v[140:143], v[58:61]
	global_load_lds_dwordx4 v8, s[98:99]
	v_mfma_f32_16x16x32_bf16 v[66:69], v[110:113], v[140:143], v[66:69]
	ds_read_b128 v[110:113], v130 offset:20480
	s_add_u32 m0, s100, 0xf000
	v_mfma_f32_16x16x32_bf16 v[144:147], v[144:147], v[140:143], v[62:65]
	global_load_lds_dwordx4 v9, s[98:99]
	v_mfma_f32_16x16x32_bf16 v[74:77], v[148:151], v[140:143], v[74:77]
	ds_read_b128 v[140:143], v130 offset:22528
	s_waitcnt lgkmcnt(3)
	v_mfma_f32_16x16x32_bf16 v[148:151], v[206:209], v[156:159], v[152:155]
	s_waitcnt lgkmcnt(2)
	v_mfma_f32_16x16x32_bf16 v[94:97], v[132:135], v[156:159], v[94:97]
	s_waitcnt lgkmcnt(1)
	v_mfma_f32_16x16x32_bf16 v[152:155], v[110:113], v[156:159], v[160:163]
	s_waitcnt lgkmcnt(0)
	v_mfma_f32_16x16x32_bf16 v[90:93], v[140:143], v[156:159], v[90:93]
	v_mfma_f32_16x16x32_bf16 v[156:159], v[206:209], v[102:105], v[164:167]
	v_mfma_f32_16x16x32_bf16 v[86:89], v[132:135], v[102:105], v[86:89]
	v_mfma_f32_16x16x32_bf16 v[160:163], v[110:113], v[102:105], v[198:201]
	v_mfma_f32_16x16x32_bf16 v[82:85], v[140:143], v[102:105], v[82:85]
	v_mfma_f32_16x16x32_bf16 v[102:105], v[206:209], v[194:197], v[202:205]
	v_mfma_f32_16x16x32_bf16 v[78:81], v[132:135], v[194:197], v[78:81]
	v_mfma_f32_16x16x32_bf16 v[164:167], v[110:113], v[194:197], v[210:213]
	v_mfma_f32_16x16x32_bf16 v[70:73], v[140:143], v[194:197], v[70:73]
	v_mfma_f32_16x16x32_bf16 v[98:101], v[206:209], v[106:109], v[98:101]
	v_mfma_f32_16x16x32_bf16 v[66:69], v[132:135], v[106:109], v[66:69]
	v_mfma_f32_16x16x32_bf16 v[110:113], v[110:113], v[106:109], v[144:147]
	v_mfma_f32_16x16x32_bf16 v[74:77], v[140:143], v[106:109], v[74:77]
	s_waitcnt vmcnt(0)
	s_setprio 0
	s_waitcnt lgkmcnt(0)
	s_barrier
	s_setprio 1
	ds_read_b128 v[26:29], v127 offset:49152
	ds_read_b128 v[10:13], v129 offset:32768
	ds_read_b128 v[30:33], v127 offset:51200
	ds_read_b128 v[132:135], v127 offset:53248
	ds_read_b128 v[140:143], v127 offset:55296
	ds_read_b128 v[18:21], v129 offset:34816
	ds_read_b128 v[106:109], v129 offset:36864
	ds_read_b128 v[122:125], v129 offset:38912
	s_add_u32 m0, s100, 0x0
	s_waitcnt lgkmcnt(6)
	v_mfma_f32_16x16x32_bf16 v[144:147], v[26:29], v[10:13], v[148:151]
	global_load_lds_dwordx4 v[180:181], off
	s_waitcnt lgkmcnt(5)
	v_mfma_f32_16x16x32_bf16 v[94:97], v[30:33], v[10:13], v[94:97]
	ds_read_b128 v[148:151], v128 offset:32768
	s_add_u32 m0, s100, 0x4000
	s_waitcnt lgkmcnt(5)
	v_mfma_f32_16x16x32_bf16 v[152:155], v[132:135], v[10:13], v[152:155]
	global_load_lds_dwordx4 v[186:187], off
	s_waitcnt lgkmcnt(4)
	v_mfma_f32_16x16x32_bf16 v[90:93], v[140:143], v[10:13], v[90:93]
	ds_read_b128 v[194:197], v128 offset:34816
	s_add_u32 m0, s100, 0x1000
	s_waitcnt lgkmcnt(4)
	v_mfma_f32_16x16x32_bf16 v[156:159], v[26:29], v[18:21], v[156:159]
	global_load_lds_dwordx4 v[114:115], off
	v_mfma_f32_16x16x32_bf16 v[86:89], v[30:33], v[18:21], v[86:89]
	ds_read_b128 v[198:201], v128 offset:36864
	s_add_u32 m0, s100, 0x5000
	v_mfma_f32_16x16x32_bf16 v[160:163], v[132:135], v[18:21], v[160:163]
	global_load_lds_dwordx4 v[174:175], off
	v_mfma_f32_16x16x32_bf16 v[82:85], v[140:143], v[18:21], v[82:85]
	ds_read_b128 v[126:129], v128 offset:38912
	s_add_u32 m0, s100, 0x2000
	s_waitcnt lgkmcnt(5)
	v_mfma_f32_16x16x32_bf16 v[202:205], v[26:29], v[106:109], v[102:105]
	global_load_lds_dwordx4 v[188:189], off
	v_mfma_f32_16x16x32_bf16 v[78:81], v[30:33], v[106:109], v[78:81]
	ds_read_b128 v[206:209], v130 offset:49152
	s_add_u32 m0, s100, 0x6000
	v_mfma_f32_16x16x32_bf16 v[164:167], v[132:135], v[106:109], v[164:167]
	global_load_lds_dwordx4 v[176:177], off
	v_mfma_f32_16x16x32_bf16 v[70:73], v[140:143], v[106:109], v[70:73]
	ds_read_b128 v[210:213], v130 offset:51200
	s_add_u32 m0, s100, 0x3000
	s_waitcnt lgkmcnt(6)
	v_mfma_f32_16x16x32_bf16 v[214:217], v[26:29], v[122:125], v[98:101]
	global_load_lds_dwordx4 v[136:137], off
	v_mfma_f32_16x16x32_bf16 v[66:69], v[30:33], v[122:125], v[66:69]
	ds_read_b128 v[218:221], v130 offset:53248
	s_add_u32 m0, s100, 0x7000
	v_mfma_f32_16x16x32_bf16 v[110:113], v[132:135], v[122:125], v[110:113]
	global_load_lds_dwordx4 v[178:179], off
	v_mfma_f32_16x16x32_bf16 v[122:125], v[140:143], v[122:125], v[74:77]
	s_waitcnt lgkmcnt(2)
	v_mfma_f32_16x16x32_bf16 v[132:135], v[206:209], v[148:151], v[144:147]
	s_waitcnt lgkmcnt(0)
	v_mfma_f32_16x16x32_bf16 v[144:147], v[218:221], v[148:151], v[152:155]
	ds_read_b128 v[152:155], v130 offset:55296
	v_mfma_f32_16x16x32_bf16 v[140:143], v[210:213], v[148:151], v[94:97]
	s_waitcnt lgkmcnt(0)
	v_mfma_f32_16x16x32_bf16 v[148:151], v[152:155], v[148:151], v[90:93]
	v_mfma_f32_16x16x32_bf16 v[98:101], v[152:155], v[194:197], v[82:85]
	v_mfma_f32_16x16x32_bf16 v[90:93], v[210:213], v[198:201], v[78:81]
	v_mfma_f32_16x16x32_bf16 v[82:85], v[152:155], v[198:201], v[70:73]
	v_mfma_f32_16x16x32_bf16 v[78:81], v[206:209], v[126:129], v[214:217]
	v_mfma_f32_16x16x32_bf16 v[74:77], v[210:213], v[126:129], v[66:69]
	v_mfma_f32_16x16x32_bf16 v[66:69], v[218:221], v[126:129], v[110:113]
	v_mfma_f32_16x16x32_bf16 v[70:73], v[152:155], v[126:129], v[122:125]
	v_mfma_f32_16x16x32_bf16 v[156:159], v[206:209], v[194:197], v[156:159]
	v_mfma_f32_16x16x32_bf16 v[106:109], v[210:213], v[194:197], v[86:89]
	v_mfma_f32_16x16x32_bf16 v[102:105], v[218:221], v[194:197], v[160:163]
	v_mfma_f32_16x16x32_bf16 v[94:97], v[206:209], v[198:201], v[202:205]
	v_mfma_f32_16x16x32_bf16 v[86:89], v[218:221], v[198:201], v[164:167]
	s_setprio 0
	v_add_u32_e32 v110, s4, v116
	v_ashrrev_i32_e32 v111, 31, v110
	v_readlane_b32 s44, v253, 18
	v_lshlrev_b64 v[112:113], 12, v[110:111]
	v_or_b32_e32 v0, s5, v117
	v_readlane_b32 s58, v253, 32
	v_readlane_b32 s59, v253, 33
	v_lshlrev_b64 v[114:115], 2, v[0:1]
	v_lshl_add_u64 v[166:167], v[110:111], 3, s[0:1]
	v_lshl_add_u64 v[112:113], s[58:59], 0, v[112:113]
	v_lshl_add_u64 v[164:165], v[112:113], 0, v[114:115]
	s_barrier
	global_load_dwordx2 v[130:131], v[166:167], off
	global_load_dwordx4 v[122:125], v[164:165], off
	v_lshl_add_u64 v[112:113], s[34:35], 0, v[114:115]
	v_lshl_add_u64 v[110:111], s[40:41], 0, v[114:115]
	global_load_dwordx4 v[126:129], v[112:113], off
	global_load_dwordx4 v[152:155], v[110:111], off
	s_mov_b32 s14, 0x3fb504f3
	global_load_dwordx4 v[160:163], v[164:165], off offset:16
	s_mov_b64 s[42:43], -1
	v_readlane_b32 s45, v253, 19
	v_readlane_b32 s46, v253, 20
	v_readlane_b32 s47, v253, 21
	v_readlane_b32 s48, v253, 22
	v_readlane_b32 s49, v253, 23
	v_readlane_b32 s50, v253, 24
	v_readlane_b32 s51, v253, 25
	v_readlane_b32 s52, v253, 26
	v_readlane_b32 s53, v253, 27
	v_readlane_b32 s54, v253, 28
	v_readlane_b32 s55, v253, 29
	v_readlane_b32 s56, v253, 30
	v_readlane_b32 s57, v253, 31
	s_waitcnt vmcnt(3)
	v_pk_add_f32 v[122:123], v[122:123], v[130:131] op_sel_hi:[1,0] neg_lo:[0,1] neg_hi:[0,1]
	v_pk_add_f32 v[124:125], v[124:125], v[130:131] op_sel_hi:[1,0] neg_lo:[0,1] neg_hi:[0,1]
	v_pk_mul_f32 v[122:123], v[122:123], v[130:131] op_sel:[0,1]
	v_pk_mul_f32 v[124:125], v[124:125], v[130:131] op_sel:[0,1]
	s_waitcnt vmcnt(1)
	v_pk_fma_f32 v[122:123], v[122:123], v[126:127], v[152:153]
	v_pk_fma_f32 v[124:125], v[124:125], v[128:129], v[154:155]
	v_pk_fma_f32 v[122:123], v[122:123], s[14:15], v[132:133] op_sel_hi:[1,0,1]
	v_pk_fma_f32 v[124:125], v[124:125], s[14:15], v[134:135] op_sel_hi:[1,0,1]
	global_store_dwordx4 v[164:165], v[122:125], off
	global_load_dwordx2 v[134:135], v[166:167], off
	global_load_dwordx4 v[126:129], v[110:111], off offset:16
	global_load_dwordx4 v[130:133], v[164:165], off offset:128
	s_waitcnt vmcnt(2)
	v_pk_add_f32 v[136:137], v[160:161], v[134:135] op_sel_hi:[1,0] neg_lo:[0,1] neg_hi:[0,1]
	global_load_dwordx4 v[122:125], v[112:113], off offset:16
	v_pk_add_f32 v[152:153], v[162:163], v[134:135] op_sel_hi:[1,0] neg_lo:[0,1] neg_hi:[0,1]
	v_pk_mul_f32 v[136:137], v[136:137], v[134:135] op_sel:[0,1]
	v_pk_mul_f32 v[134:135], v[152:153], v[134:135] op_sel:[0,1]
	s_waitcnt vmcnt(0)
	v_pk_fma_f32 v[122:123], v[136:137], v[122:123], v[126:127]
	v_pk_fma_f32 v[124:125], v[134:135], v[124:125], v[128:129]
	v_pk_fma_f32 v[122:123], v[122:123], s[14:15], v[140:141] op_sel_hi:[1,0,1]
	v_pk_fma_f32 v[124:125], v[124:125], s[14:15], v[142:143] op_sel_hi:[1,0,1]
	global_store_dwordx4 v[164:165], v[122:125], off offset:16
	global_load_dwordx2 v[140:141], v[166:167], off
	global_load_dwordx4 v[126:129], v[110:111], off offset:128
	global_load_dwordx4 v[134:137], v[164:165], off offset:144
	s_waitcnt vmcnt(2)
	v_pk_add_f32 v[130:131], v[130:131], v[140:141] op_sel_hi:[1,0] neg_lo:[0,1] neg_hi:[0,1]
	global_load_dwordx4 v[122:125], v[112:113], off offset:128
	v_pk_add_f32 v[132:133], v[132:133], v[140:141] op_sel_hi:[1,0] neg_lo:[0,1] neg_hi:[0,1]
	v_pk_mul_f32 v[130:131], v[130:131], v[140:141] op_sel:[0,1]
	v_pk_mul_f32 v[132:133], v[132:133], v[140:141] op_sel:[0,1]
	s_waitcnt vmcnt(0)
	v_pk_fma_f32 v[122:123], v[130:131], v[122:123], v[126:127]
	v_pk_fma_f32 v[124:125], v[132:133], v[124:125], v[128:129]
	v_pk_fma_f32 v[122:123], v[122:123], s[14:15], v[144:145] op_sel_hi:[1,0,1]
	v_pk_fma_f32 v[124:125], v[124:125], s[14:15], v[146:147] op_sel_hi:[1,0,1]
	global_store_dwordx4 v[164:165], v[122:125], off offset:128
	global_load_dwordx2 v[140:141], v[166:167], off
	global_load_dwordx4 v[126:129], v[110:111], off offset:144
	v_add_u32_e32 v130, s4, v118
	global_load_dwordx4 v[122:125], v[112:113], off offset:144
	v_ashrrev_i32_e32 v131, 31, v130
	v_lshlrev_b64 v[132:133], 12, v[130:131]
	v_lshl_add_u64 v[142:143], v[130:131], 3, s[0:1]
	v_lshl_add_u64 v[130:131], s[58:59], 0, v[132:133]
	v_lshl_add_u64 v[144:145], v[130:131], 0, v[114:115]
	global_load_dwordx4 v[130:133], v[144:145], off
	s_waitcnt vmcnt(3)
	v_pk_add_f32 v[134:135], v[134:135], v[140:141] op_sel_hi:[1,0] neg_lo:[0,1] neg_hi:[0,1]
	v_pk_add_f32 v[136:137], v[136:137], v[140:141] op_sel_hi:[1,0] neg_lo:[0,1] neg_hi:[0,1]
	v_pk_mul_f32 v[134:135], v[134:135], v[140:141] op_sel:[0,1]
	v_pk_mul_f32 v[136:137], v[136:137], v[140:141] op_sel:[0,1]
	s_waitcnt vmcnt(1)
	v_pk_fma_f32 v[122:123], v[134:135], v[122:123], v[126:127]
	v_pk_fma_f32 v[124:125], v[136:137], v[124:125], v[128:129]
	v_pk_fma_f32 v[122:123], v[122:123], s[14:15], v[148:149] op_sel_hi:[1,0,1]
	v_pk_fma_f32 v[124:125], v[124:125], s[14:15], v[150:151] op_sel_hi:[1,0,1]
	global_store_dwordx4 v[164:165], v[122:125], off offset:144
	global_load_dwordx2 v[140:141], v[142:143], off
	global_load_dwordx4 v[126:129], v[110:111], off
	global_load_dwordx4 v[134:137], v[144:145], off offset:16
	s_waitcnt vmcnt(2)
	v_pk_add_f32 v[130:131], v[130:131], v[140:141] op_sel_hi:[1,0] neg_lo:[0,1] neg_hi:[0,1]
	global_load_dwordx4 v[122:125], v[112:113], off
	v_pk_add_f32 v[132:133], v[132:133], v[140:141] op_sel_hi:[1,0] neg_lo:[0,1] neg_hi:[0,1]
	v_pk_mul_f32 v[130:131], v[130:131], v[140:141] op_sel:[0,1]
	v_pk_mul_f32 v[132:133], v[132:133], v[140:141] op_sel:[0,1]
	s_waitcnt vmcnt(0)
	v_pk_fma_f32 v[122:123], v[130:131], v[122:123], v[126:127]
	v_pk_fma_f32 v[124:125], v[132:133], v[124:125], v[128:129]
	v_pk_fma_f32 v[122:123], v[122:123], s[14:15], v[156:157] op_sel_hi:[1,0,1]
	v_pk_fma_f32 v[124:125], v[124:125], s[14:15], v[158:159] op_sel_hi:[1,0,1]
	global_store_dwordx4 v[144:145], v[122:125], off
	global_load_dwordx2 v[140:141], v[142:143], off
	global_load_dwordx4 v[126:129], v[110:111], off offset:16
	global_load_dwordx4 v[130:133], v[144:145], off offset:128
	s_waitcnt vmcnt(2)
	v_pk_add_f32 v[134:135], v[134:135], v[140:141] op_sel_hi:[1,0] neg_lo:[0,1] neg_hi:[0,1]
	global_load_dwordx4 v[122:125], v[112:113], off offset:16
	v_pk_add_f32 v[136:137], v[136:137], v[140:141] op_sel_hi:[1,0] neg_lo:[0,1] neg_hi:[0,1]
	v_pk_mul_f32 v[134:135], v[134:135], v[140:141] op_sel:[0,1]
	v_pk_mul_f32 v[136:137], v[136:137], v[140:141] op_sel:[0,1]
	s_waitcnt vmcnt(0)
	v_pk_fma_f32 v[122:123], v[134:135], v[122:123], v[126:127]
	v_pk_fma_f32 v[124:125], v[136:137], v[124:125], v[128:129]
	v_pk_fma_f32 v[106:107], v[122:123], s[14:15], v[106:107] op_sel_hi:[1,0,1]
	v_pk_fma_f32 v[108:109], v[124:125], s[14:15], v[108:109] op_sel_hi:[1,0,1]
	global_store_dwordx4 v[144:145], v[106:109], off offset:16
	global_load_dwordx2 v[134:135], v[142:143], off
	global_load_dwordx4 v[122:125], v[110:111], off offset:128
	global_load_dwordx4 v[126:129], v[144:145], off offset:144
	s_waitcnt vmcnt(2)
	v_pk_add_f32 v[130:131], v[130:131], v[134:135] op_sel_hi:[1,0] neg_lo:[0,1] neg_hi:[0,1]
	global_load_dwordx4 v[106:109], v[112:113], off offset:128
	v_pk_add_f32 v[132:133], v[132:133], v[134:135] op_sel_hi:[1,0] neg_lo:[0,1] neg_hi:[0,1]
	v_pk_mul_f32 v[130:131], v[130:131], v[134:135] op_sel:[0,1]
	v_pk_mul_f32 v[132:133], v[132:133], v[134:135] op_sel:[0,1]
	s_waitcnt vmcnt(0)
	v_pk_fma_f32 v[106:107], v[130:131], v[106:107], v[122:123]
	v_pk_fma_f32 v[108:109], v[132:133], v[108:109], v[124:125]
	v_pk_fma_f32 v[102:103], v[106:107], s[14:15], v[102:103] op_sel_hi:[1,0,1]
	v_pk_fma_f32 v[104:105], v[108:109], s[14:15], v[104:105] op_sel_hi:[1,0,1]
	global_store_dwordx4 v[144:145], v[102:105], off offset:128
	global_load_dwordx2 v[130:131], v[142:143], off
	global_load_dwordx4 v[106:109], v[110:111], off offset:144
	v_add_u32_e32 v122, s4, v119
	global_load_dwordx4 v[102:105], v[112:113], off offset:144
	v_ashrrev_i32_e32 v123, 31, v122
	v_lshlrev_b64 v[124:125], 12, v[122:123]
	v_lshl_add_u64 v[132:133], v[122:123], 3, s[0:1]
	v_lshl_add_u64 v[122:123], s[58:59], 0, v[124:125]
	v_lshl_add_u64 v[134:135], v[122:123], 0, v[114:115]
	global_load_dwordx4 v[122:125], v[134:135], off
	s_waitcnt vmcnt(3)
	v_pk_add_f32 v[126:127], v[126:127], v[130:131] op_sel_hi:[1,0] neg_lo:[0,1] neg_hi:[0,1]
	v_pk_add_f32 v[128:129], v[128:129], v[130:131] op_sel_hi:[1,0] neg_lo:[0,1] neg_hi:[0,1]
	v_pk_mul_f32 v[126:127], v[126:127], v[130:131] op_sel:[0,1]
	v_pk_mul_f32 v[128:129], v[128:129], v[130:131] op_sel:[0,1]
	s_waitcnt vmcnt(1)
	v_pk_fma_f32 v[102:103], v[126:127], v[102:103], v[106:107]
	v_pk_fma_f32 v[104:105], v[128:129], v[104:105], v[108:109]
	v_pk_fma_f32 v[98:99], v[102:103], s[14:15], v[98:99] op_sel_hi:[1,0,1]
	v_pk_fma_f32 v[100:101], v[104:105], s[14:15], v[100:101] op_sel_hi:[1,0,1]
	global_store_dwordx4 v[144:145], v[98:101], off offset:144
	global_load_dwordx2 v[126:127], v[132:133], off
	global_load_dwordx4 v[102:105], v[110:111], off
	global_load_dwordx4 v[106:109], v[134:135], off offset:16
	s_waitcnt vmcnt(2)
	v_pk_add_f32 v[122:123], v[122:123], v[126:127] op_sel_hi:[1,0] neg_lo:[0,1] neg_hi:[0,1]
	global_load_dwordx4 v[98:101], v[112:113], off
	v_pk_add_f32 v[124:125], v[124:125], v[126:127] op_sel_hi:[1,0] neg_lo:[0,1] neg_hi:[0,1]
	v_pk_mul_f32 v[122:123], v[122:123], v[126:127] op_sel:[0,1]
	v_pk_mul_f32 v[124:125], v[124:125], v[126:127] op_sel:[0,1]
	s_waitcnt vmcnt(0)
	v_pk_fma_f32 v[98:99], v[122:123], v[98:99], v[102:103]
	v_pk_fma_f32 v[100:101], v[124:125], v[100:101], v[104:105]
	v_pk_fma_f32 v[94:95], v[98:99], s[14:15], v[94:95] op_sel_hi:[1,0,1]
	v_pk_fma_f32 v[96:97], v[100:101], s[14:15], v[96:97] op_sel_hi:[1,0,1]
	global_store_dwordx4 v[134:135], v[94:97], off
	global_load_dwordx2 v[122:123], v[132:133], off
	global_load_dwordx4 v[98:101], v[110:111], off offset:16
	global_load_dwordx4 v[102:105], v[134:135], off offset:128
	s_waitcnt vmcnt(2)
	v_pk_add_f32 v[106:107], v[106:107], v[122:123] op_sel_hi:[1,0] neg_lo:[0,1] neg_hi:[0,1]
	global_load_dwordx4 v[94:97], v[112:113], off offset:16
	v_pk_add_f32 v[108:109], v[108:109], v[122:123] op_sel_hi:[1,0] neg_lo:[0,1] neg_hi:[0,1]
	v_pk_mul_f32 v[106:107], v[106:107], v[122:123] op_sel:[0,1]
	v_pk_mul_f32 v[108:109], v[108:109], v[122:123] op_sel:[0,1]
	s_waitcnt vmcnt(0)
	v_pk_fma_f32 v[94:95], v[106:107], v[94:95], v[98:99]
	v_pk_fma_f32 v[96:97], v[108:109], v[96:97], v[100:101]
	v_pk_fma_f32 v[90:91], v[94:95], s[14:15], v[90:91] op_sel_hi:[1,0,1]
	v_pk_fma_f32 v[92:93], v[96:97], s[14:15], v[92:93] op_sel_hi:[1,0,1]
	global_store_dwordx4 v[134:135], v[90:93], off offset:16
	global_load_dwordx2 v[106:107], v[132:133], off
	global_load_dwordx4 v[94:97], v[110:111], off offset:128
	global_load_dwordx4 v[98:101], v[134:135], off offset:144
	s_waitcnt vmcnt(2)
	v_pk_add_f32 v[102:103], v[102:103], v[106:107] op_sel_hi:[1,0] neg_lo:[0,1] neg_hi:[0,1]
	global_load_dwordx4 v[90:93], v[112:113], off offset:128
	v_pk_add_f32 v[104:105], v[104:105], v[106:107] op_sel_hi:[1,0] neg_lo:[0,1] neg_hi:[0,1]
	v_pk_mul_f32 v[102:103], v[102:103], v[106:107] op_sel:[0,1]
	v_pk_mul_f32 v[104:105], v[104:105], v[106:107] op_sel:[0,1]
	s_waitcnt vmcnt(0)
	v_pk_fma_f32 v[90:91], v[102:103], v[90:91], v[94:95]
	v_pk_fma_f32 v[92:93], v[104:105], v[92:93], v[96:97]
	v_pk_fma_f32 v[86:87], v[90:91], s[14:15], v[86:87] op_sel_hi:[1,0,1]
	v_pk_fma_f32 v[88:89], v[92:93], s[14:15], v[88:89] op_sel_hi:[1,0,1]
	global_store_dwordx4 v[134:135], v[86:89], off offset:128
	global_load_dwordx2 v[102:103], v[132:133], off
	global_load_dwordx4 v[90:93], v[110:111], off offset:144
	v_add_u32_e32 v94, s4, v120
	global_load_dwordx4 v[86:89], v[112:113], off offset:144
	v_ashrrev_i32_e32 v95, 31, v94
	v_lshlrev_b64 v[96:97], 12, v[94:95]
	v_lshl_add_u64 v[104:105], v[94:95], 3, s[0:1]
	v_lshl_add_u64 v[94:95], s[58:59], 0, v[96:97]
	v_lshl_add_u64 v[106:107], v[94:95], 0, v[114:115]
	global_load_dwordx4 v[94:97], v[106:107], off
	s_waitcnt vmcnt(3)
	v_pk_add_f32 v[98:99], v[98:99], v[102:103] op_sel_hi:[1,0] neg_lo:[0,1] neg_hi:[0,1]
	v_pk_add_f32 v[100:101], v[100:101], v[102:103] op_sel_hi:[1,0] neg_lo:[0,1] neg_hi:[0,1]
	v_pk_mul_f32 v[98:99], v[98:99], v[102:103] op_sel:[0,1]
	v_pk_mul_f32 v[100:101], v[100:101], v[102:103] op_sel:[0,1]
	s_waitcnt vmcnt(1)
	v_pk_fma_f32 v[86:87], v[98:99], v[86:87], v[90:91]
	v_pk_fma_f32 v[88:89], v[100:101], v[88:89], v[92:93]
	v_pk_fma_f32 v[82:83], v[86:87], s[14:15], v[82:83] op_sel_hi:[1,0,1]
	v_pk_fma_f32 v[84:85], v[88:89], s[14:15], v[84:85] op_sel_hi:[1,0,1]
	global_store_dwordx4 v[134:135], v[82:85], off offset:144
	global_load_dwordx2 v[98:99], v[104:105], off
	global_load_dwordx4 v[86:89], v[110:111], off
	global_load_dwordx4 v[90:93], v[106:107], off offset:16
	s_waitcnt vmcnt(2)
	v_pk_add_f32 v[94:95], v[94:95], v[98:99] op_sel_hi:[1,0] neg_lo:[0,1] neg_hi:[0,1]
	global_load_dwordx4 v[82:85], v[112:113], off
	v_pk_add_f32 v[96:97], v[96:97], v[98:99] op_sel_hi:[1,0] neg_lo:[0,1] neg_hi:[0,1]
	v_pk_mul_f32 v[94:95], v[94:95], v[98:99] op_sel:[0,1]
	v_pk_mul_f32 v[96:97], v[96:97], v[98:99] op_sel:[0,1]
	s_waitcnt vmcnt(0)
	v_pk_fma_f32 v[82:83], v[94:95], v[82:83], v[86:87]
	v_pk_fma_f32 v[84:85], v[96:97], v[84:85], v[88:89]
	v_pk_fma_f32 v[78:79], v[82:83], s[14:15], v[78:79] op_sel_hi:[1,0,1]
	v_pk_fma_f32 v[80:81], v[84:85], s[14:15], v[80:81] op_sel_hi:[1,0,1]
	global_store_dwordx4 v[106:107], v[78:81], off
	global_load_dwordx2 v[94:95], v[104:105], off
	global_load_dwordx4 v[82:85], v[110:111], off offset:16
	global_load_dwordx4 v[86:89], v[106:107], off offset:128
	s_waitcnt vmcnt(2)
	v_pk_add_f32 v[90:91], v[90:91], v[94:95] op_sel_hi:[1,0] neg_lo:[0,1] neg_hi:[0,1]
	global_load_dwordx4 v[78:81], v[112:113], off offset:16
	v_pk_add_f32 v[92:93], v[92:93], v[94:95] op_sel_hi:[1,0] neg_lo:[0,1] neg_hi:[0,1]
	v_pk_mul_f32 v[90:91], v[90:91], v[94:95] op_sel:[0,1]
	v_pk_mul_f32 v[92:93], v[92:93], v[94:95] op_sel:[0,1]
	s_waitcnt vmcnt(0)
	v_pk_fma_f32 v[78:79], v[90:91], v[78:79], v[82:83]
	v_pk_fma_f32 v[80:81], v[92:93], v[80:81], v[84:85]
	v_pk_fma_f32 v[74:75], v[78:79], s[14:15], v[74:75] op_sel_hi:[1,0,1]
	v_pk_fma_f32 v[76:77], v[80:81], s[14:15], v[76:77] op_sel_hi:[1,0,1]
	global_store_dwordx4 v[106:107], v[74:77], off offset:16
	global_load_dwordx2 v[90:91], v[104:105], off
	global_load_dwordx4 v[78:81], v[110:111], off offset:128
	global_load_dwordx4 v[82:85], v[106:107], off offset:144
	s_waitcnt vmcnt(2)
	v_pk_add_f32 v[86:87], v[86:87], v[90:91] op_sel_hi:[1,0] neg_lo:[0,1] neg_hi:[0,1]
	global_load_dwordx4 v[74:77], v[112:113], off offset:128
	v_pk_add_f32 v[88:89], v[88:89], v[90:91] op_sel_hi:[1,0] neg_lo:[0,1] neg_hi:[0,1]
	v_pk_mul_f32 v[86:87], v[86:87], v[90:91] op_sel:[0,1]
	v_pk_mul_f32 v[88:89], v[88:89], v[90:91] op_sel:[0,1]
	s_waitcnt vmcnt(0)
	v_pk_fma_f32 v[74:75], v[86:87], v[74:75], v[78:79]
	v_pk_fma_f32 v[76:77], v[88:89], v[76:77], v[80:81]
	v_pk_fma_f32 v[66:67], v[74:75], s[14:15], v[66:67] op_sel_hi:[1,0,1]
	v_pk_fma_f32 v[68:69], v[76:77], s[14:15], v[68:69] op_sel_hi:[1,0,1]
	global_store_dwordx4 v[106:107], v[66:69], off offset:128
	global_load_dwordx2 v[78:79], v[104:105], off
	global_load_dwordx4 v[74:77], v[110:111], off offset:144
	s_waitcnt vmcnt(1)
	v_pk_add_f32 v[80:81], v[82:83], v[78:79] op_sel_hi:[1,0] neg_lo:[0,1] neg_hi:[0,1]
	global_load_dwordx4 v[66:69], v[112:113], off offset:144
	v_pk_add_f32 v[82:83], v[84:85], v[78:79] op_sel_hi:[1,0] neg_lo:[0,1] neg_hi:[0,1]
	v_pk_mul_f32 v[80:81], v[80:81], v[78:79] op_sel:[0,1]
	v_pk_mul_f32 v[78:79], v[82:83], v[78:79] op_sel:[0,1]
	s_waitcnt vmcnt(0)
	v_pk_fma_f32 v[66:67], v[80:81], v[66:67], v[74:75]
	v_pk_fma_f32 v[68:69], v[78:79], v[68:69], v[76:77]
	v_pk_fma_f32 v[66:67], v[66:67], s[14:15], v[70:71] op_sel_hi:[1,0,1]
	v_pk_fma_f32 v[68:69], v[68:69], s[14:15], v[72:73] op_sel_hi:[1,0,1]
	global_store_dwordx4 v[106:107], v[66:69], off offset:144
	s_cmp_lg_u32 s101, 0
	s_cbranch_scc1 .LBB0_126
	v_mov_b32_e32 v0, v169
	v_mov_b32_e32 v67, v169
	s_movk_i32 s4, 0xb00
	v_lshrrev_b32_e32 v66, 3, v0
	v_lshrrev_b32_e32 v69, 3, v67
	v_add_u32_e32 v66, s9, v66
	v_add_u32_e32 v69, s10, v69
	v_lshlrev_b32_e32 v0, 3, v0
	v_mul_lo_u32 v66, v66, s4
	v_lshlrev_b32_e32 v67, 3, v67
	v_mul_lo_u32 v69, v69, s4
	v_and_or_b32 v0, v0, 56, v66
	v_and_or_b32 v72, v67, 56, v69
	v_add_u32_e32 v66, 0x16000, v0
	v_add_u32_e32 v68, 0x2c000, v0
	v_add_u32_e32 v70, 0x42000, v0
	v_add_u32_e32 v74, 0x16000, v72
	v_add_u32_e32 v76, 0x2c000, v72
	v_add_u32_e32 v78, 0x42000, v72
	s_mov_b64 s[42:43], 0
	s_branch .LBB0_126

.LBB0_137:
	s_setprio 1
	s_add_u32 s98, s46, s16
	s_addc_u32 s99, s47, 0
	s_add_u32 s98, s98, 0x80
	s_addc_u32 s99, s99, 0
	ds_read_b128 v[132:135], v128 offset:16384
	ds_read_b128 v[140:143], v130
	ds_read_b128 v[152:155], v128 offset:18432
	ds_read_b128 v[160:163], v128 offset:20480
	ds_read_b128 v[164:167], v128 offset:22528
	ds_read_b128 v[144:147], v130 offset:2048
	ds_read_b128 v[148:151], v130 offset:4096
	ds_read_b128 v[156:159], v130 offset:6144
	s_add_u32 m0, s100, 0x8000
	s_waitcnt lgkmcnt(6)
	v_mfma_f32_16x16x32_bf16 v[34:37], v[132:135], v[140:143], v[34:37]
	global_load_lds_dwordx4 v194, s[98:99]
	s_waitcnt lgkmcnt(5)
	v_mfma_f32_16x16x32_bf16 v[94:97], v[152:155], v[140:143], v[94:97]
	ds_read_b128 v[198:201], v129
	s_add_u32 m0, s100, 0xc000
	s_waitcnt lgkmcnt(5)
	v_mfma_f32_16x16x32_bf16 v[38:41], v[160:163], v[140:143], v[38:41]
	global_load_lds_dwordx4 v195, s[98:99]
	s_waitcnt lgkmcnt(4)
	v_mfma_f32_16x16x32_bf16 v[90:93], v[164:167], v[140:143], v[90:93]
	ds_read_b128 v[140:143], v129 offset:2048
	s_add_u32 m0, s100, 0x9000
	s_waitcnt lgkmcnt(4)
	v_mfma_f32_16x16x32_bf16 v[42:45], v[132:135], v[144:147], v[42:45]
	global_load_lds_dwordx4 v196, s[98:99]
	v_mfma_f32_16x16x32_bf16 v[86:89], v[152:155], v[144:147], v[86:89]
	ds_read_b128 v[210:213], v129 offset:4096
	s_add_u32 m0, s100, 0xd000
	v_mfma_f32_16x16x32_bf16 v[46:49], v[160:163], v[144:147], v[46:49]
	global_load_lds_dwordx4 v197, s[98:99]
	v_mfma_f32_16x16x32_bf16 v[82:85], v[164:167], v[144:147], v[82:85]
	ds_read_b128 v[144:147], v129 offset:6144
	s_add_u32 m0, s100, 0xa000
	s_waitcnt lgkmcnt(5)
	v_mfma_f32_16x16x32_bf16 v[50:53], v[132:135], v[148:151], v[50:53]
	global_load_lds_dwordx4 v202, s[98:99]
	v_mfma_f32_16x16x32_bf16 v[78:81], v[152:155], v[148:151], v[78:81]
	ds_read_b128 v[222:225], v131 offset:16384
	s_add_u32 m0, s100, 0xe000
	v_mfma_f32_16x16x32_bf16 v[54:57], v[160:163], v[148:151], v[54:57]
	global_load_lds_dwordx4 v203, s[98:99]
	v_mfma_f32_16x16x32_bf16 v[70:73], v[164:167], v[148:151], v[70:73]
	ds_read_b128 v[148:151], v131 offset:18432
	s_add_u32 m0, s100, 0xb000
	s_waitcnt lgkmcnt(6)
	v_mfma_f32_16x16x32_bf16 v[58:61], v[132:135], v[156:159], v[58:61]
	global_load_lds_dwordx4 v204, s[98:99]
	v_mfma_f32_16x16x32_bf16 v[66:69], v[152:155], v[156:159], v[66:69]
	ds_read_b128 v[152:155], v131 offset:20480
	s_add_u32 m0, s100, 0xf000
	v_mfma_f32_16x16x32_bf16 v[62:65], v[160:163], v[156:159], v[62:65]
	global_load_lds_dwordx4 v205, s[98:99]
	v_mfma_f32_16x16x32_bf16 v[74:77], v[164:167], v[156:159], v[74:77]
	ds_read_b128 v[156:159], v131 offset:22528
	s_waitcnt lgkmcnt(3)
	v_mfma_f32_16x16x32_bf16 v[34:37], v[222:225], v[198:201], v[34:37]
	s_waitcnt lgkmcnt(2)
	v_mfma_f32_16x16x32_bf16 v[94:97], v[148:151], v[198:201], v[94:97]
	s_waitcnt lgkmcnt(1)
	v_mfma_f32_16x16x32_bf16 v[38:41], v[152:155], v[198:201], v[38:41]
	s_waitcnt lgkmcnt(0)
	v_mfma_f32_16x16x32_bf16 v[90:93], v[156:159], v[198:201], v[90:93]
	v_mfma_f32_16x16x32_bf16 v[42:45], v[222:225], v[140:143], v[42:45]
	v_mfma_f32_16x16x32_bf16 v[86:89], v[148:151], v[140:143], v[86:89]
	v_mfma_f32_16x16x32_bf16 v[46:49], v[152:155], v[140:143], v[46:49]
	v_mfma_f32_16x16x32_bf16 v[82:85], v[156:159], v[140:143], v[82:85]
	v_mfma_f32_16x16x32_bf16 v[50:53], v[222:225], v[210:213], v[50:53]
	v_mfma_f32_16x16x32_bf16 v[78:81], v[148:151], v[210:213], v[78:81]
	v_mfma_f32_16x16x32_bf16 v[54:57], v[152:155], v[210:213], v[54:57]
	v_mfma_f32_16x16x32_bf16 v[70:73], v[156:159], v[210:213], v[70:73]
	v_mfma_f32_16x16x32_bf16 v[58:61], v[222:225], v[144:147], v[58:61]
	v_mfma_f32_16x16x32_bf16 v[66:69], v[148:151], v[144:147], v[66:69]
	v_mfma_f32_16x16x32_bf16 v[62:65], v[152:155], v[144:147], v[62:65]
	v_mfma_f32_16x16x32_bf16 v[74:77], v[156:159], v[144:147], v[74:77]
	s_waitcnt vmcnt(0)
	s_setprio 0
	s_waitcnt lgkmcnt(0)
	s_barrier
	s_setprio 1
	s_add_u32 s98, s98, 0x80
	s_addc_u32 s99, s99, 0
	ds_read_b128 v[26:29], v128 offset:49152
	ds_read_b128 v[10:13], v130 offset:32768
	ds_read_b128 v[30:33], v128 offset:51200
	ds_read_b128 v[148:151], v128 offset:53248
	ds_read_b128 v[152:155], v128 offset:55296
	ds_read_b128 v[18:21], v130 offset:34816
	ds_read_b128 v[140:143], v130 offset:36864
	ds_read_b128 v[144:147], v130 offset:38912
	s_add_u32 m0, s100, 0x0
	s_waitcnt lgkmcnt(6)
	v_mfma_f32_16x16x32_bf16 v[34:37], v[26:29], v[10:13], v[34:37]
	global_load_lds_dwordx4 v194, s[98:99]
	s_waitcnt lgkmcnt(5)
	v_mfma_f32_16x16x32_bf16 v[94:97], v[30:33], v[10:13], v[94:97]
	ds_read_b128 v[156:159], v129 offset:32768
	s_add_u32 m0, s100, 0x4000
	s_waitcnt lgkmcnt(5)
	v_mfma_f32_16x16x32_bf16 v[38:41], v[148:151], v[10:13], v[38:41]
	global_load_lds_dwordx4 v195, s[98:99]
	s_waitcnt lgkmcnt(4)
	v_mfma_f32_16x16x32_bf16 v[90:93], v[152:155], v[10:13], v[90:93]
	ds_read_b128 v[164:167], v129 offset:34816
	s_add_u32 m0, s100, 0x1000
	s_waitcnt lgkmcnt(4)
	v_mfma_f32_16x16x32_bf16 v[42:45], v[26:29], v[18:21], v[42:45]
	global_load_lds_dwordx4 v196, s[98:99]
	v_mfma_f32_16x16x32_bf16 v[86:89], v[30:33], v[18:21], v[86:89]
	ds_read_b128 v[198:201], v129 offset:36864
	s_add_u32 m0, s100, 0x5000
	v_mfma_f32_16x16x32_bf16 v[46:49], v[148:151], v[18:21], v[46:49]
	global_load_lds_dwordx4 v197, s[98:99]
	v_mfma_f32_16x16x32_bf16 v[82:85], v[152:155], v[18:21], v[82:85]
	ds_read_b128 v[210:213], v129 offset:38912
	s_add_u32 m0, s100, 0x2000
	s_waitcnt lgkmcnt(5)
	v_mfma_f32_16x16x32_bf16 v[50:53], v[26:29], v[140:143], v[50:53]
	global_load_lds_dwordx4 v202, s[98:99]
	v_mfma_f32_16x16x32_bf16 v[78:81], v[30:33], v[140:143], v[78:81]
	ds_read_b128 v[222:225], v131 offset:49152
	s_add_u32 m0, s100, 0x6000
	v_mfma_f32_16x16x32_bf16 v[54:57], v[148:151], v[140:143], v[54:57]
	global_load_lds_dwordx4 v203, s[98:99]
	v_mfma_f32_16x16x32_bf16 v[70:73], v[152:155], v[140:143], v[70:73]
	ds_read_b128 v[140:143], v131 offset:51200
	s_add_u32 m0, s100, 0x3000
	s_waitcnt lgkmcnt(6)
	v_mfma_f32_16x16x32_bf16 v[58:61], v[26:29], v[144:147], v[58:61]
	global_load_lds_dwordx4 v204, s[98:99]
	v_mfma_f32_16x16x32_bf16 v[66:69], v[30:33], v[144:147], v[66:69]
	ds_read_b128 v[230:233], v131 offset:53248
	s_add_u32 m0, s100, 0x7000
	v_mfma_f32_16x16x32_bf16 v[62:65], v[148:151], v[144:147], v[62:65]
	global_load_lds_dwordx4 v205, s[98:99]
	v_mfma_f32_16x16x32_bf16 v[74:77], v[152:155], v[144:147], v[74:77]
	ds_read_b128 v[144:147], v131 offset:55296
	s_waitcnt lgkmcnt(3)
	v_mfma_f32_16x16x32_bf16 v[34:37], v[222:225], v[156:159], v[34:37]
	s_waitcnt lgkmcnt(2)
	v_mfma_f32_16x16x32_bf16 v[94:97], v[140:143], v[156:159], v[94:97]
	s_waitcnt lgkmcnt(1)
	v_mfma_f32_16x16x32_bf16 v[38:41], v[230:233], v[156:159], v[38:41]
	s_waitcnt lgkmcnt(0)
	v_mfma_f32_16x16x32_bf16 v[90:93], v[144:147], v[156:159], v[90:93]
	v_mfma_f32_16x16x32_bf16 v[42:45], v[222:225], v[164:167], v[42:45]
	v_mfma_f32_16x16x32_bf16 v[86:89], v[140:143], v[164:167], v[86:89]
	v_mfma_f32_16x16x32_bf16 v[46:49], v[230:233], v[164:167], v[46:49]
	v_mfma_f32_16x16x32_bf16 v[82:85], v[144:147], v[164:167], v[82:85]
	v_mfma_f32_16x16x32_bf16 v[50:53], v[222:225], v[198:201], v[50:53]
	v_mfma_f32_16x16x32_bf16 v[78:81], v[140:143], v[198:201], v[78:81]
	v_mfma_f32_16x16x32_bf16 v[54:57], v[230:233], v[198:201], v[54:57]
	v_mfma_f32_16x16x32_bf16 v[70:73], v[144:147], v[198:201], v[70:73]
	v_mfma_f32_16x16x32_bf16 v[58:61], v[222:225], v[210:213], v[58:61]
	v_mfma_f32_16x16x32_bf16 v[66:69], v[140:143], v[210:213], v[66:69]
	v_mfma_f32_16x16x32_bf16 v[62:65], v[230:233], v[210:213], v[62:65]
	v_mfma_f32_16x16x32_bf16 v[74:77], v[144:147], v[210:213], v[74:77]
	s_waitcnt vmcnt(0)
	s_setprio 0
	s_add_i32 s9, s9, 2
	s_add_u32 s46, s46, 0x100
	s_addc_u32 s47, s47, 0
	s_cmp_lt_u32 s9, 12
	s_waitcnt lgkmcnt(0)
	s_barrier
	s_cbranch_scc1 .LBB0_137
	v_mov_b32_e32 v2, v194
	v_mov_b32_e32 v3, v195
	v_mov_b32_e32 v4, v196
	v_mov_b32_e32 v5, v197
	v_mov_b32_e32 v6, v202
	v_mov_b32_e32 v7, v203
	v_mov_b32_e32 v8, v204
	v_mov_b32_e32 v9, v205
	s_add_u32 s98, s46, s16
	s_addc_u32 s99, s47, 0
	s_add_u32 s98, s98, 0x80
	s_addc_u32 s99, s99, 0
	s_add_i32 s9, s8, s2
	s_cmpk_lt_u32 s9, 0x580
	s_cselect_b32 s8, s9, s8
	s_mul_hi_u32 s10, s8, 0xba2e8ba3
	s_lshr_b32 s10, s10, 8
	s_mul_i32 s11, s10, 0x160
	v_mov_b32_e32 v0, v169
	s_sub_i32 s11, s8, s11
	s_lshl_b32 s8, s10, 3
	s_add_i32 s8, s8, s21
	s_and_b32 s10, s11, 7
	v_lshlrev_b32_e32 v100, 3, v0
	v_lshlrev_b32_e32 v0, 7, v0
	s_or_b32 s8, s8, s10
	v_and_b32_e32 v0, 0xfffffc00, v0
	v_lshl_add_u32 v0, s8, 17, v0
	v_and_or_b32 v0, v100, 56, v0
	v_mov_b32_e32 v100, v169
	s_lshl_b32 s10, s11, 4
	s_and_b32 s10, s10, 0x1f80
	v_lshrrev_b32_e32 v101, 3, v100
	v_lshlrev_b32_e32 v100, 3, v100
	v_add_u32_e32 v101, s10, v101
	v_and_b32_e32 v100, 56, v100
	v_lshl_or_b32 v160, v101, 10, v100
	s_cmpk_gt_u32 s9, 0x57f
	s_cselect_b32 s101, 1, 0
	v_add_u32_e32 v116, 0x8000, v0
	v_add_u32_e32 v136, 0x10000, v0
	v_add_u32_e32 v174, 0x18000, v0
	v_add_u32_e32 v176, 0x8000, v160
	v_add_u32_e32 v178, 0x10000, v160
	v_add_u32_e32 v180, 0x18000, v160
	s_setprio 1
	ds_read_b128 v[100:103], v128 offset:16384
	ds_read_b128 v[104:107], v130
	ds_read_b128 v[112:115], v128 offset:18432
	ds_read_b128 v[140:143], v128 offset:20480
	ds_read_b128 v[144:147], v128 offset:22528
	ds_read_b128 v[108:111], v130 offset:2048
	ds_read_b128 v[124:127], v130 offset:4096
	ds_read_b128 v[132:135], v130 offset:6144
	v_lshrrev_b32_e32 v14, 3, v169
	v_and_b32_e32 v15, 3, v14
	v_bfe_u32 v16, v14, 4, 1
	v_lshl_or_b32 v15, v16, 2, v15
	v_bfe_u32 v16, v14, 2, 1
	v_lshl_or_b32 v15, v16, 3, v15
	v_bfe_u32 v16, v14, 3, 1
	v_lshl_or_b32 v15, v16, 4, v15
	v_sub_u32_e32 v15, v15, v14
	v_mul_i32_i24_e32 v15, 0x400, v15
	v_and_b32_e32 v14, 7, v14
	v_lshlrev_b32_e32 v14, 3, v14
	v_xor_b32_e32 v0, v0, v14
	v_add_u32_e32 v160, v160, v15
	v_xor_b32_e32 v160, v160, v14
	v_xor_b32_e32 v116, v116, v14
	v_add_u32_e32 v176, v176, v15
	v_xor_b32_e32 v176, v176, v14
	v_xor_b32_e32 v136, v136, v14
	v_add_u32_e32 v178, v178, v15
	v_xor_b32_e32 v178, v178, v14
	v_xor_b32_e32 v174, v174, v14
	v_add_u32_e32 v180, v180, v15
	v_xor_b32_e32 v180, v180, v14
	v_mov_b32_e32 v161, v1
	v_mov_b32_e32 v117, v1
	v_mov_b32_e32 v177, v1
	v_mov_b32_e32 v137, v1
	v_mov_b32_e32 v179, v1
	v_mov_b32_e32 v175, v1
	v_mov_b32_e32 v181, v1
	v_lshl_add_u64 v[186:187], v[0:1], 1, s[38:39]
	v_lshl_add_u64 v[188:189], v[160:161], 1, s[42:43]
	v_lshl_add_u64 v[116:117], v[116:117], 1, s[38:39]
	v_lshl_add_u64 v[176:177], v[176:177], 1, s[42:43]
	v_lshl_add_u64 v[136:137], v[136:137], 1, s[38:39]
	v_lshl_add_u64 v[178:179], v[178:179], 1, s[42:43]
	v_lshl_add_u64 v[174:175], v[174:175], 1, s[38:39]
	v_lshl_add_u64 v[180:181], v[180:181], 1, s[42:43]
	s_add_u32 m0, s100, 0x8000
	s_waitcnt lgkmcnt(6)
	v_mfma_f32_16x16x32_bf16 v[148:151], v[100:103], v[104:107], v[34:37]
	global_load_lds_dwordx4 v2, s[98:99]
	s_waitcnt lgkmcnt(5)
	v_mfma_f32_16x16x32_bf16 v[94:97], v[112:115], v[104:107], v[94:97]
	ds_read_b128 v[152:155], v129
	s_add_u32 m0, s100, 0xc000
	s_waitcnt lgkmcnt(5)
	v_mfma_f32_16x16x32_bf16 v[156:159], v[140:143], v[104:107], v[38:41]
	global_load_lds_dwordx4 v3, s[98:99]
	s_waitcnt lgkmcnt(4)
	v_mfma_f32_16x16x32_bf16 v[90:93], v[144:147], v[104:107], v[90:93]
	ds_read_b128 v[104:107], v129 offset:2048
	s_add_u32 m0, s100, 0x9000
	s_waitcnt lgkmcnt(4)
	v_mfma_f32_16x16x32_bf16 v[160:163], v[100:103], v[108:111], v[42:45]
	global_load_lds_dwordx4 v4, s[98:99]
	v_mfma_f32_16x16x32_bf16 v[86:89], v[112:115], v[108:111], v[86:89]
	ds_read_b128 v[164:167], v129 offset:4096
	s_add_u32 m0, s100, 0xd000
	v_mfma_f32_16x16x32_bf16 v[194:197], v[140:143], v[108:111], v[46:49]
	global_load_lds_dwordx4 v5, s[98:99]
	v_mfma_f32_16x16x32_bf16 v[82:85], v[144:147], v[108:111], v[82:85]
	ds_read_b128 v[108:111], v129 offset:6144
	s_add_u32 m0, s100, 0xa000
	s_waitcnt lgkmcnt(5)
	v_mfma_f32_16x16x32_bf16 v[198:201], v[100:103], v[124:127], v[50:53]
	global_load_lds_dwordx4 v6, s[98:99]
	v_mfma_f32_16x16x32_bf16 v[78:81], v[112:115], v[124:127], v[78:81]
	ds_read_b128 v[202:205], v131 offset:16384
	s_add_u32 m0, s100, 0xe000
	v_mfma_f32_16x16x32_bf16 v[206:209], v[140:143], v[124:127], v[54:57]
	global_load_lds_dwordx4 v7, s[98:99]
	v_mfma_f32_16x16x32_bf16 v[70:73], v[144:147], v[124:127], v[70:73]
	ds_read_b128 v[124:127], v131 offset:18432
	s_add_u32 m0, s100, 0xb000
	s_waitcnt lgkmcnt(6)
	v_mfma_f32_16x16x32_bf16 v[100:103], v[100:103], v[132:135], v[58:61]
	global_load_lds_dwordx4 v8, s[98:99]
	v_mfma_f32_16x16x32_bf16 v[66:69], v[112:115], v[132:135], v[66:69]
	ds_read_b128 v[112:115], v131 offset:20480
	s_add_u32 m0, s100, 0xf000
	v_mfma_f32_16x16x32_bf16 v[140:143], v[140:143], v[132:135], v[62:65]
	global_load_lds_dwordx4 v9, s[98:99]
	v_mfma_f32_16x16x32_bf16 v[74:77], v[144:147], v[132:135], v[74:77]
	ds_read_b128 v[132:135], v131 offset:22528
	s_waitcnt lgkmcnt(3)
	v_mfma_f32_16x16x32_bf16 v[144:147], v[202:205], v[152:155], v[148:151]
	s_waitcnt lgkmcnt(2)
	v_mfma_f32_16x16x32_bf16 v[94:97], v[124:127], v[152:155], v[94:97]
	s_waitcnt lgkmcnt(1)
	v_mfma_f32_16x16x32_bf16 v[148:151], v[112:115], v[152:155], v[156:159]
	s_waitcnt lgkmcnt(0)
	v_mfma_f32_16x16x32_bf16 v[90:93], v[132:135], v[152:155], v[90:93]
	v_mfma_f32_16x16x32_bf16 v[152:155], v[202:205], v[104:107], v[160:163]
	v_mfma_f32_16x16x32_bf16 v[86:89], v[124:127], v[104:107], v[86:89]
	v_mfma_f32_16x16x32_bf16 v[156:159], v[112:115], v[104:107], v[194:197]
	v_mfma_f32_16x16x32_bf16 v[82:85], v[132:135], v[104:107], v[82:85]
	v_mfma_f32_16x16x32_bf16 v[104:107], v[202:205], v[164:167], v[198:201]
	v_mfma_f32_16x16x32_bf16 v[78:81], v[124:127], v[164:167], v[78:81]
	v_mfma_f32_16x16x32_bf16 v[160:163], v[112:115], v[164:167], v[206:209]
	v_mfma_f32_16x16x32_bf16 v[70:73], v[132:135], v[164:167], v[70:73]
	v_mfma_f32_16x16x32_bf16 v[100:103], v[202:205], v[108:111], v[100:103]
	v_mfma_f32_16x16x32_bf16 v[66:69], v[124:127], v[108:111], v[66:69]
	v_mfma_f32_16x16x32_bf16 v[112:115], v[112:115], v[108:111], v[140:143]
	v_mfma_f32_16x16x32_bf16 v[74:77], v[132:135], v[108:111], v[74:77]
	s_waitcnt vmcnt(0)
	s_setprio 0
	s_waitcnt lgkmcnt(0)
	s_barrier
	s_setprio 1
	ds_read_b128 v[26:29], v128 offset:49152
	ds_read_b128 v[10:13], v130 offset:32768
	ds_read_b128 v[30:33], v128 offset:51200
	ds_read_b128 v[132:135], v128 offset:53248
	ds_read_b128 v[140:143], v128 offset:55296
	ds_read_b128 v[18:21], v130 offset:34816
	ds_read_b128 v[108:111], v130 offset:36864
	ds_read_b128 v[124:127], v130 offset:38912
	s_add_u32 m0, s100, 0x0
	s_waitcnt lgkmcnt(6)
	v_mfma_f32_16x16x32_bf16 v[144:147], v[26:29], v[10:13], v[144:147]
	global_load_lds_dwordx4 v[186:187], off
	s_waitcnt lgkmcnt(5)
	v_mfma_f32_16x16x32_bf16 v[94:97], v[30:33], v[10:13], v[94:97]
	ds_read_b128 v[164:167], v129 offset:32768
	s_add_u32 m0, s100, 0x4000
	s_waitcnt lgkmcnt(5)
	v_mfma_f32_16x16x32_bf16 v[148:151], v[132:135], v[10:13], v[148:151]
	global_load_lds_dwordx4 v[188:189], off
	s_waitcnt lgkmcnt(4)
	v_mfma_f32_16x16x32_bf16 v[90:93], v[140:143], v[10:13], v[90:93]
	ds_read_b128 v[194:197], v129 offset:34816
	s_add_u32 m0, s100, 0x1000
	s_waitcnt lgkmcnt(4)
	v_mfma_f32_16x16x32_bf16 v[152:155], v[26:29], v[18:21], v[152:155]
	global_load_lds_dwordx4 v[116:117], off
	v_mfma_f32_16x16x32_bf16 v[86:89], v[30:33], v[18:21], v[86:89]
	ds_read_b128 v[198:201], v129 offset:36864
	s_add_u32 m0, s100, 0x5000
	v_mfma_f32_16x16x32_bf16 v[156:159], v[132:135], v[18:21], v[156:159]
	global_load_lds_dwordx4 v[176:177], off
	v_mfma_f32_16x16x32_bf16 v[82:85], v[140:143], v[18:21], v[82:85]
	ds_read_b128 v[202:205], v129 offset:38912
	s_add_u32 m0, s100, 0x2000
	s_waitcnt lgkmcnt(5)
	v_mfma_f32_16x16x32_bf16 v[104:107], v[26:29], v[108:111], v[104:107]
	global_load_lds_dwordx4 v[136:137], off
	v_mfma_f32_16x16x32_bf16 v[78:81], v[30:33], v[108:111], v[78:81]
	ds_read_b128 v[206:209], v131 offset:49152
	s_add_u32 m0, s100, 0x6000
	v_mfma_f32_16x16x32_bf16 v[160:163], v[132:135], v[108:111], v[160:163]
	global_load_lds_dwordx4 v[178:179], off
	v_mfma_f32_16x16x32_bf16 v[70:73], v[140:143], v[108:111], v[70:73]
	ds_read_b128 v[108:111], v131 offset:51200
	s_add_u32 m0, s100, 0x3000
	s_waitcnt lgkmcnt(6)
	v_mfma_f32_16x16x32_bf16 v[100:103], v[26:29], v[124:127], v[100:103]
	global_load_lds_dwordx4 v[174:175], off
	v_mfma_f32_16x16x32_bf16 v[66:69], v[30:33], v[124:127], v[66:69]
	ds_read_b128 v[210:213], v131 offset:53248
	s_add_u32 m0, s100, 0x7000
	v_mfma_f32_16x16x32_bf16 v[112:115], v[132:135], v[124:127], v[112:115]
	global_load_lds_dwordx4 v[180:181], off
	v_mfma_f32_16x16x32_bf16 v[124:127], v[140:143], v[124:127], v[74:77]
	ds_read_b128 v[128:131], v131 offset:55296
	s_waitcnt lgkmcnt(3)
	v_mfma_f32_16x16x32_bf16 v[132:135], v[206:209], v[164:167], v[144:147]
	s_waitcnt lgkmcnt(2)
	v_mfma_f32_16x16x32_bf16 v[140:143], v[108:111], v[164:167], v[94:97]
	s_waitcnt lgkmcnt(1)
	v_mfma_f32_16x16x32_bf16 v[144:147], v[210:213], v[164:167], v[148:151]
	s_waitcnt lgkmcnt(0)
	v_mfma_f32_16x16x32_bf16 v[148:151], v[128:131], v[164:167], v[90:93]
	v_mfma_f32_16x16x32_bf16 v[152:155], v[206:209], v[194:197], v[152:155]
	v_mfma_f32_16x16x32_bf16 v[164:167], v[108:111], v[194:197], v[86:89]
	v_mfma_f32_16x16x32_bf16 v[156:159], v[210:213], v[194:197], v[156:159]
	v_mfma_f32_16x16x32_bf16 v[194:197], v[128:131], v[194:197], v[82:85]
	v_mfma_f32_16x16x32_bf16 v[94:97], v[206:209], v[198:201], v[104:107]
	v_mfma_f32_16x16x32_bf16 v[86:89], v[108:111], v[198:201], v[78:81]
	v_mfma_f32_16x16x32_bf16 v[90:93], v[210:213], v[198:201], v[160:163]
	v_mfma_f32_16x16x32_bf16 v[82:85], v[128:131], v[198:201], v[70:73]
	v_mfma_f32_16x16x32_bf16 v[74:77], v[206:209], v[202:205], v[100:103]
	v_mfma_f32_16x16x32_bf16 v[66:69], v[108:111], v[202:205], v[66:69]
	v_mfma_f32_16x16x32_bf16 v[70:73], v[210:213], v[202:205], v[112:115]
	v_mfma_f32_16x16x32_bf16 v[78:81], v[128:131], v[202:205], v[124:127]
	s_setprio 0
	v_mul_f32_e32 v0, 0xbfb8aa3b, v132
	v_exp_f32_e32 v0, v0
	v_mul_f32_e32 v99, 0xbfb8aa3b, v133
	v_exp_f32_e32 v99, v99
	v_mul_f32_e32 v101, 0xbfb8aa3b, v135
	v_add_f32_e32 v0, 1.0, v0
	v_rcp_f32_e32 v100, v0
	v_add_f32_e32 v0, 1.0, v99
	v_mul_f32_e32 v99, 0xbfb8aa3b, v134
	v_exp_f32_e32 v99, v99
	v_exp_f32_e32 v103, v101
	v_rcp_f32_e32 v101, v0
	v_mul_f32_e32 v108, 0xbfb8aa3b, v152
	v_add_f32_e32 v0, 1.0, v99
	v_mul_f32_e32 v99, 0xbfb8aa3b, v140
	v_rcp_f32_e32 v102, v0
	v_add_f32_e32 v0, 1.0, v103
	v_exp_f32_e32 v99, v99
	v_mul_f32_e32 v103, 0xbfb8aa3b, v141
	v_exp_f32_e32 v105, v103
	v_rcp_f32_e32 v103, v0
	v_add_f32_e32 v0, 1.0, v99
	v_mul_f32_e32 v99, 0xbfb8aa3b, v142
	v_rcp_f32_e32 v104, v0
	v_add_f32_e32 v0, 1.0, v105
	v_exp_f32_e32 v99, v99
	v_mul_f32_e32 v105, 0xbfb8aa3b, v143
	v_exp_f32_e32 v107, v105
	v_rcp_f32_e32 v105, v0
	v_add_f32_e32 v0, 1.0, v99
	v_rcp_f32_e32 v106, v0
	v_add_f32_e32 v0, 1.0, v107
	v_rcp_f32_e32 v107, v0
	v_pk_mul_f32 v[100:101], v[132:133], v[100:101]
	v_pk_mul_f32 v[102:103], v[134:135], v[102:103]
	v_pk_mul_f32 v[100:101], v[144:145], v[100:101]
	v_pk_mul_f32 v[102:103], v[146:147], v[102:103]
	v_cvt_pk_bf16_f32 v100, v100, v101
	v_cvt_pk_bf16_f32 v101, v102, v103
	v_pk_mul_f32 v[102:103], v[140:141], v[104:105]
	v_pk_mul_f32 v[104:105], v[142:143], v[106:107]
	v_pk_mul_f32 v[102:103], v[148:149], v[102:103]
	v_pk_mul_f32 v[104:105], v[150:151], v[104:105]
	v_add_u32_e32 v0, s4, v118
	v_cvt_pk_bf16_f32 v102, v102, v103
	v_cvt_pk_bf16_f32 v103, v104, v105
	v_mov_b64_e32 v[104:105], s[44:45]
	v_mad_i64_i32 v[106:107], s[14:15], v0, s20, v[104:105]
	v_or_b32_e32 v0, s5, v119
	v_mul_f32_e32 v109, 0xbfb8aa3b, v153
	v_lshl_add_u64 v[106:107], v[106:107], 0, v[0:1]
	v_mov_b32_e32 v99, v1
	v_exp_f32_e32 v108, v108
	v_exp_f32_e32 v109, v109
	v_lshl_add_u64 v[106:107], v[106:107], 0, v[98:99]
	s_barrier
	global_store_dwordx4 v[106:107], v[100:103], off
	v_mul_f32_e32 v106, 0xbfb8aa3b, v164
	v_mul_f32_e32 v107, 0xbfb8aa3b, v165
	v_mul_f32_e32 v102, 0xbfb8aa3b, v154
	v_mul_f32_e32 v103, 0xbfb8aa3b, v155
	v_exp_f32_e32 v102, v102
	v_exp_f32_e32 v103, v103
	v_add_f32_e32 v100, 1.0, v108
	v_add_f32_e32 v101, 1.0, v109
	v_mul_f32_e32 v108, 0xbfb8aa3b, v166
	v_mul_f32_e32 v109, 0xbfb8aa3b, v167
	v_exp_f32_e32 v106, v106
	v_exp_f32_e32 v107, v107
	v_exp_f32_e32 v108, v108
	v_exp_f32_e32 v109, v109
	v_add_f32_e32 v102, 1.0, v102
	v_add_f32_e32 v103, 1.0, v103
	v_rcp_f32_e32 v100, v100
	v_rcp_f32_e32 v101, v101
	v_rcp_f32_e32 v102, v102
	v_rcp_f32_e32 v103, v103
	v_add_f32_e32 v106, 1.0, v106
	v_add_f32_e32 v107, 1.0, v107
	v_add_f32_e32 v108, 1.0, v108
	v_add_f32_e32 v109, 1.0, v109
	v_rcp_f32_e32 v106, v106
	v_rcp_f32_e32 v107, v107
	v_rcp_f32_e32 v108, v108
	v_rcp_f32_e32 v109, v109
	v_pk_mul_f32 v[100:101], v[152:153], v[100:101]
	v_pk_mul_f32 v[102:103], v[154:155], v[102:103]
	v_pk_mul_f32 v[100:101], v[156:157], v[100:101]
	v_pk_mul_f32 v[102:103], v[158:159], v[102:103]
	v_cvt_pk_bf16_f32 v100, v100, v101
	v_cvt_pk_bf16_f32 v101, v102, v103
	v_pk_mul_f32 v[102:103], v[164:165], v[106:107]
	v_pk_mul_f32 v[106:107], v[166:167], v[108:109]
	v_add_u32_e32 v110, s4, v120
	v_pk_mul_f32 v[102:103], v[194:195], v[102:103]
	v_pk_mul_f32 v[106:107], v[196:197], v[106:107]
	v_cvt_pk_bf16_f32 v102, v102, v103
	v_cvt_pk_bf16_f32 v103, v106, v107
	v_mad_i64_i32 v[106:107], s[14:15], v110, s20, v[104:105]
	v_mul_f32_e32 v108, 0xbfb8aa3b, v94
	v_mul_f32_e32 v109, 0xbfb8aa3b, v95
	v_lshl_add_u64 v[106:107], v[106:107], 0, v[0:1]
	v_exp_f32_e32 v108, v108
	v_exp_f32_e32 v109, v109
	v_lshl_add_u64 v[106:107], v[106:107], 0, v[98:99]
	global_store_dwordx4 v[106:107], v[100:103], off
	v_mul_f32_e32 v106, 0xbfb8aa3b, v86
	v_mul_f32_e32 v107, 0xbfb8aa3b, v87
	v_mul_f32_e32 v102, 0xbfb8aa3b, v96
	v_mul_f32_e32 v103, 0xbfb8aa3b, v97
	v_exp_f32_e32 v102, v102
	v_exp_f32_e32 v103, v103
	v_exp_f32_e32 v106, v106
	v_exp_f32_e32 v107, v107
	v_add_f32_e32 v100, 1.0, v108
	v_add_f32_e32 v101, 1.0, v109
	v_mul_f32_e32 v108, 0xbfb8aa3b, v88
	v_mul_f32_e32 v109, 0xbfb8aa3b, v89
	v_exp_f32_e32 v108, v108
	v_exp_f32_e32 v109, v109
	v_rcp_f32_e32 v100, v100
	v_rcp_f32_e32 v101, v101
	v_add_f32_e32 v102, 1.0, v102
	v_add_f32_e32 v103, 1.0, v103
	v_add_f32_e32 v106, 1.0, v106
	v_add_f32_e32 v107, 1.0, v107
	v_rcp_f32_e32 v102, v102
	v_rcp_f32_e32 v103, v103
	v_rcp_f32_e32 v106, v106
	v_rcp_f32_e32 v107, v107
	v_add_f32_e32 v108, 1.0, v108
	v_add_f32_e32 v109, 1.0, v109
	v_rcp_f32_e32 v108, v108
	v_rcp_f32_e32 v109, v109
	v_pk_mul_f32 v[94:95], v[94:95], v[100:101]
	v_pk_mul_f32 v[86:87], v[86:87], v[106:107]
	v_pk_mul_f32 v[90:91], v[90:91], v[94:95]
	v_pk_mul_f32 v[94:95], v[96:97], v[102:103]
	v_pk_mul_f32 v[82:83], v[82:83], v[86:87]
	v_pk_mul_f32 v[92:93], v[92:93], v[94:95]
	v_cvt_pk_bf16_f32 v90, v90, v91
	v_cvt_pk_bf16_f32 v91, v92, v93
	v_cvt_pk_bf16_f32 v92, v82, v83
	v_pk_mul_f32 v[82:83], v[88:89], v[108:109]
	v_add_u32_e32 v110, s4, v121
	v_pk_mul_f32 v[82:83], v[84:85], v[82:83]
	v_mul_f32_e32 v84, 0xbfb8aa3b, v74
	v_mul_f32_e32 v85, 0xbfb8aa3b, v75
	v_exp_f32_e32 v84, v84
	v_exp_f32_e32 v85, v85
	v_cvt_pk_bf16_f32 v93, v82, v83
	v_mad_i64_i32 v[82:83], s[14:15], v110, s20, v[104:105]
	v_lshl_add_u64 v[82:83], v[82:83], 0, v[0:1]
	v_lshl_add_u64 v[82:83], v[82:83], 0, v[98:99]
	global_store_dwordx4 v[82:83], v[90:93], off
	v_add_f32_e32 v82, 1.0, v84
	v_add_f32_e32 v83, 1.0, v85
	v_mul_f32_e32 v84, 0xbfb8aa3b, v76
	v_mul_f32_e32 v85, 0xbfb8aa3b, v77
	v_mul_f32_e32 v86, 0xbfb8aa3b, v66
	v_mul_f32_e32 v87, 0xbfb8aa3b, v67
	v_exp_f32_e32 v84, v84
	v_exp_f32_e32 v85, v85
	v_exp_f32_e32 v86, v86
	v_exp_f32_e32 v87, v87
	v_mul_f32_e32 v88, 0xbfb8aa3b, v68
	v_mul_f32_e32 v89, 0xbfb8aa3b, v69
	v_exp_f32_e32 v88, v88
	v_exp_f32_e32 v89, v89
	v_rcp_f32_e32 v82, v82
	v_rcp_f32_e32 v83, v83
	v_add_f32_e32 v84, 1.0, v84
	v_add_f32_e32 v85, 1.0, v85
	v_add_f32_e32 v86, 1.0, v86
	v_add_f32_e32 v87, 1.0, v87
	v_rcp_f32_e32 v84, v84
	v_rcp_f32_e32 v85, v85
	v_rcp_f32_e32 v86, v86
	v_rcp_f32_e32 v87, v87
	v_add_f32_e32 v88, 1.0, v88
	v_add_f32_e32 v89, 1.0, v89
	v_rcp_f32_e32 v88, v88
	v_rcp_f32_e32 v89, v89
	v_pk_mul_f32 v[74:75], v[74:75], v[82:83]
	v_pk_mul_f32 v[66:67], v[66:67], v[86:87]
	v_pk_mul_f32 v[70:71], v[70:71], v[74:75]
	v_pk_mul_f32 v[74:75], v[76:77], v[84:85]
	v_pk_mul_f32 v[66:67], v[78:79], v[66:67]
	v_pk_mul_f32 v[72:73], v[72:73], v[74:75]
	v_cvt_pk_bf16_f32 v70, v70, v71
	v_cvt_pk_bf16_f32 v71, v72, v73
	v_cvt_pk_bf16_f32 v72, v66, v67
	v_pk_mul_f32 v[66:67], v[68:69], v[88:89]
	v_add_u32_e32 v90, s4, v122
	v_pk_mul_f32 v[66:67], v[80:81], v[66:67]
	s_nop 0
	v_cvt_pk_bf16_f32 v73, v66, v67
	v_mad_i64_i32 v[66:67], s[4:5], v90, s20, v[104:105]
	v_lshl_add_u64 v[66:67], v[66:67], 0, v[0:1]
	v_lshl_add_u64 v[66:67], v[66:67], 0, v[98:99]
	global_store_dwordx4 v[66:67], v[70:73], off
	s_cmp_lg_u32 s101, 0
	s_cbranch_scc0 .LBB0_135

.LBB0_157:
	s_setprio 1
	s_add_u32 s98, s38, s36
	s_addc_u32 s99, s39, 0
	s_add_u32 s98, s98, 0x80
	s_addc_u32 s99, s99, 0
	v_add_u32_e32 v122, v119, v118
	v_add_u32_e32 v124, v119, v120
	v_add_u32_e32 v123, v121, v120
	ds_read_b128 v[126:129], v122 offset:16384
	ds_read_b128 v[144:147], v122 offset:18432
	ds_read_b128 v[158:161], v122 offset:20480
	ds_read_b128 v[162:165], v122 offset:22528
	ds_read_b128 v[130:133], v124
	ds_read_b128 v[134:137], v124 offset:2048
	ds_read_b128 v[140:143], v124 offset:4096
	ds_read_b128 v[148:151], v124 offset:6144
	s_add_u32 m0, s100, 0x8000
	s_waitcnt lgkmcnt(3)
	v_mfma_f32_16x16x32_bf16 v[34:37], v[126:129], v[130:133], v[34:37]
	global_load_lds_dwordx4 v194, s[98:99]
	v_mfma_f32_16x16x32_bf16 v[94:97], v[144:147], v[130:133], v[94:97]
	ds_read_b128 v[198:201], v123
	s_add_u32 m0, s100, 0xc000
	v_mfma_f32_16x16x32_bf16 v[38:41], v[158:161], v[130:133], v[38:41]
	global_load_lds_dwordx4 v195, s[98:99]
	v_mfma_f32_16x16x32_bf16 v[90:93], v[162:165], v[130:133], v[90:93]
	ds_read_b128 v[206:209], v123 offset:2048
	s_add_u32 m0, s100, 0x9000
	s_waitcnt lgkmcnt(4)
	v_mfma_f32_16x16x32_bf16 v[42:45], v[126:129], v[134:137], v[42:45]
	global_load_lds_dwordx4 v196, s[98:99]
	v_mfma_f32_16x16x32_bf16 v[86:89], v[144:147], v[134:137], v[86:89]
	ds_read_b128 v[214:217], v123 offset:4096
	s_add_u32 m0, s100, 0xd000
	v_mfma_f32_16x16x32_bf16 v[46:49], v[158:161], v[134:137], v[46:49]
	global_load_lds_dwordx4 v197, s[98:99]
	v_mfma_f32_16x16x32_bf16 v[82:85], v[162:165], v[134:137], v[82:85]
	v_add_u32_e32 v130, v121, v118
	ds_read_b128 v[132:135], v123 offset:6144
	s_add_u32 m0, s100, 0xa000
	s_waitcnt lgkmcnt(5)
	v_mfma_f32_16x16x32_bf16 v[50:53], v[126:129], v[140:143], v[50:53]
	global_load_lds_dwordx4 v202, s[98:99]
	v_mfma_f32_16x16x32_bf16 v[78:81], v[144:147], v[140:143], v[78:81]
	ds_read_b128 v[226:229], v130 offset:16384
	s_add_u32 m0, s100, 0xe000
	v_mfma_f32_16x16x32_bf16 v[54:57], v[158:161], v[140:143], v[54:57]
	global_load_lds_dwordx4 v203, s[98:99]
	v_mfma_f32_16x16x32_bf16 v[70:73], v[162:165], v[140:143], v[70:73]
	ds_read_b128 v[140:143], v130 offset:18432
	s_add_u32 m0, s100, 0xb000
	s_waitcnt lgkmcnt(6)
	v_mfma_f32_16x16x32_bf16 v[58:61], v[126:129], v[148:151], v[58:61]
	global_load_lds_dwordx4 v204, s[98:99]
	v_mfma_f32_16x16x32_bf16 v[66:69], v[144:147], v[148:151], v[66:69]
	ds_read_b128 v[144:147], v130 offset:20480
	s_add_u32 m0, s100, 0xf000
	v_mfma_f32_16x16x32_bf16 v[62:65], v[158:161], v[148:151], v[62:65]
	global_load_lds_dwordx4 v205, s[98:99]
	v_mfma_f32_16x16x32_bf16 v[74:77], v[162:165], v[148:151], v[74:77]
	ds_read_b128 v[148:151], v130 offset:22528
	s_waitcnt lgkmcnt(3)
	v_mfma_f32_16x16x32_bf16 v[34:37], v[226:229], v[198:201], v[34:37]
	s_waitcnt lgkmcnt(2)
	v_mfma_f32_16x16x32_bf16 v[94:97], v[140:143], v[198:201], v[94:97]
	s_waitcnt lgkmcnt(1)
	v_mfma_f32_16x16x32_bf16 v[38:41], v[144:147], v[198:201], v[38:41]
	s_waitcnt lgkmcnt(0)
	v_mfma_f32_16x16x32_bf16 v[90:93], v[148:151], v[198:201], v[90:93]
	v_mfma_f32_16x16x32_bf16 v[42:45], v[226:229], v[206:209], v[42:45]
	v_mfma_f32_16x16x32_bf16 v[86:89], v[140:143], v[206:209], v[86:89]
	v_mfma_f32_16x16x32_bf16 v[46:49], v[144:147], v[206:209], v[46:49]
	v_mfma_f32_16x16x32_bf16 v[82:85], v[148:151], v[206:209], v[82:85]
	v_mfma_f32_16x16x32_bf16 v[50:53], v[226:229], v[214:217], v[50:53]
	v_mfma_f32_16x16x32_bf16 v[78:81], v[140:143], v[214:217], v[78:81]
	v_mfma_f32_16x16x32_bf16 v[54:57], v[144:147], v[214:217], v[54:57]
	v_mfma_f32_16x16x32_bf16 v[70:73], v[148:151], v[214:217], v[70:73]
	v_mfma_f32_16x16x32_bf16 v[58:61], v[226:229], v[132:135], v[58:61]
	v_mfma_f32_16x16x32_bf16 v[66:69], v[140:143], v[132:135], v[66:69]
	v_mfma_f32_16x16x32_bf16 v[62:65], v[144:147], v[132:135], v[62:65]
	v_mfma_f32_16x16x32_bf16 v[74:77], v[148:151], v[132:135], v[74:77]
	s_waitcnt vmcnt(0)
	s_setprio 0
	s_waitcnt lgkmcnt(0)
	s_barrier
	s_setprio 1
	s_add_u32 s98, s98, 0x80
	s_addc_u32 s99, s99, 0
	ds_read_b128 v[26:29], v122 offset:49152
	ds_read_b128 v[10:13], v124 offset:32768
	ds_read_b128 v[30:33], v122 offset:51200
	ds_read_b128 v[144:147], v122 offset:53248
	ds_read_b128 v[148:151], v122 offset:55296
	ds_read_b128 v[18:21], v124 offset:34816
	ds_read_b128 v[132:135], v124 offset:36864
	ds_read_b128 v[140:143], v124 offset:38912
	s_add_u32 m0, s100, 0x0
	s_waitcnt lgkmcnt(6)
	v_mfma_f32_16x16x32_bf16 v[34:37], v[26:29], v[10:13], v[34:37]
	global_load_lds_dwordx4 v194, s[98:99]
	s_waitcnt lgkmcnt(5)
	v_mfma_f32_16x16x32_bf16 v[94:97], v[30:33], v[10:13], v[94:97]
	ds_read_b128 v[162:165], v123 offset:32768
	s_add_u32 m0, s100, 0x4000
	s_waitcnt lgkmcnt(5)
	v_mfma_f32_16x16x32_bf16 v[38:41], v[144:147], v[10:13], v[38:41]
	global_load_lds_dwordx4 v195, s[98:99]
	s_waitcnt lgkmcnt(4)
	v_mfma_f32_16x16x32_bf16 v[90:93], v[148:151], v[10:13], v[90:93]
	ds_read_b128 v[198:201], v123 offset:34816
	s_add_u32 m0, s100, 0x1000
	s_waitcnt lgkmcnt(4)
	v_mfma_f32_16x16x32_bf16 v[42:45], v[26:29], v[18:21], v[42:45]
	global_load_lds_dwordx4 v196, s[98:99]
	v_mfma_f32_16x16x32_bf16 v[86:89], v[30:33], v[18:21], v[86:89]
	ds_read_b128 v[206:209], v123 offset:36864
	s_add_u32 m0, s100, 0x5000
	v_mfma_f32_16x16x32_bf16 v[46:49], v[144:147], v[18:21], v[46:49]
	global_load_lds_dwordx4 v197, s[98:99]
	v_mfma_f32_16x16x32_bf16 v[82:85], v[148:151], v[18:21], v[82:85]
	ds_read_b128 v[214:217], v123 offset:38912
	s_add_u32 m0, s100, 0x2000
	s_waitcnt lgkmcnt(5)
	v_mfma_f32_16x16x32_bf16 v[50:53], v[26:29], v[132:135], v[50:53]
	global_load_lds_dwordx4 v202, s[98:99]
	v_mfma_f32_16x16x32_bf16 v[78:81], v[30:33], v[132:135], v[78:81]
	ds_read_b128 v[226:229], v130 offset:49152
	s_add_u32 m0, s100, 0x6000
	v_mfma_f32_16x16x32_bf16 v[54:57], v[144:147], v[132:135], v[54:57]
	global_load_lds_dwordx4 v203, s[98:99]
	v_mfma_f32_16x16x32_bf16 v[70:73], v[148:151], v[132:135], v[70:73]
	ds_read_b128 v[132:135], v130 offset:51200
	s_add_u32 m0, s100, 0x3000
	s_waitcnt lgkmcnt(6)
	v_mfma_f32_16x16x32_bf16 v[58:61], v[26:29], v[140:143], v[58:61]
	global_load_lds_dwordx4 v204, s[98:99]
	v_mfma_f32_16x16x32_bf16 v[66:69], v[30:33], v[140:143], v[66:69]
	ds_read_b128 v[234:237], v130 offset:53248
	s_add_u32 m0, s100, 0x7000
	v_mfma_f32_16x16x32_bf16 v[62:65], v[144:147], v[140:143], v[62:65]
	global_load_lds_dwordx4 v205, s[98:99]
	v_mfma_f32_16x16x32_bf16 v[74:77], v[148:151], v[140:143], v[74:77]
	ds_read_b128 v[140:143], v130 offset:55296
	s_waitcnt lgkmcnt(3)
	v_mfma_f32_16x16x32_bf16 v[34:37], v[226:229], v[162:165], v[34:37]
	s_waitcnt lgkmcnt(2)
	v_mfma_f32_16x16x32_bf16 v[94:97], v[132:135], v[162:165], v[94:97]
	s_waitcnt lgkmcnt(1)
	v_mfma_f32_16x16x32_bf16 v[38:41], v[234:237], v[162:165], v[38:41]
	s_waitcnt lgkmcnt(0)
	v_mfma_f32_16x16x32_bf16 v[90:93], v[140:143], v[162:165], v[90:93]
	v_mfma_f32_16x16x32_bf16 v[42:45], v[226:229], v[198:201], v[42:45]
	v_mfma_f32_16x16x32_bf16 v[86:89], v[132:135], v[198:201], v[86:89]
	v_mfma_f32_16x16x32_bf16 v[46:49], v[234:237], v[198:201], v[46:49]
	v_mfma_f32_16x16x32_bf16 v[82:85], v[140:143], v[198:201], v[82:85]
	v_mfma_f32_16x16x32_bf16 v[50:53], v[226:229], v[206:209], v[50:53]
	v_mfma_f32_16x16x32_bf16 v[78:81], v[132:135], v[206:209], v[78:81]
	v_mfma_f32_16x16x32_bf16 v[54:57], v[234:237], v[206:209], v[54:57]
	v_mfma_f32_16x16x32_bf16 v[70:73], v[140:143], v[206:209], v[70:73]
	v_mfma_f32_16x16x32_bf16 v[58:61], v[226:229], v[214:217], v[58:61]
	v_mfma_f32_16x16x32_bf16 v[66:69], v[132:135], v[214:217], v[66:69]
	v_mfma_f32_16x16x32_bf16 v[62:65], v[234:237], v[214:217], v[62:65]
	v_mfma_f32_16x16x32_bf16 v[74:77], v[140:143], v[214:217], v[74:77]
	s_waitcnt vmcnt(0)
	s_setprio 0
	s_add_i32 s5, s5, 2
	s_add_u32 s38, s38, 0x100
	s_addc_u32 s39, s39, 0
	s_cmp_lt_u32 s5, 12
	s_waitcnt lgkmcnt(0)
	s_barrier
	s_cbranch_scc1 .LBB0_157
	v_mov_b32_e32 v2, v194
	v_mov_b32_e32 v3, v195
	v_mov_b32_e32 v4, v196
	v_mov_b32_e32 v5, v197
	v_mov_b32_e32 v6, v202
	v_mov_b32_e32 v7, v203
	v_mov_b32_e32 v8, v204
	v_mov_b32_e32 v9, v205
	s_add_u32 s98, s38, s36
	s_addc_u32 s99, s39, 0
	s_add_u32 s98, s98, 0x80
	s_addc_u32 s99, s99, 0
	s_add_i32 s5, s11, s2
	s_cmpk_lt_u32 s5, 0x100
	s_cselect_b64 s[44:45], -1, 0
	s_and_b64 s[8:9], s[44:45], exec
	s_cselect_b32 s9, s5, s11
	s_lshr_b32 s8, s9, 3
	s_and_b32 s8, s8, 0x1fffff8
	s_add_i32 s8, s8, s21
	s_and_b32 s11, s9, 7
	v_mov_b32_e32 v0, v169
	s_or_b32 s8, s8, s11
	s_lshl_b32 s8, s8, 7
	v_lshrrev_b32_e32 v98, 3, v0
	v_lshlrev_b32_e32 v0, 3, v0
	v_add_u32_e32 v98, s8, v98
	v_and_b32_e32 v0, 56, v0
	v_lshl_or_b32 v0, v98, 10, v0
	v_mov_b32_e32 v98, v169
	s_lshl_b32 s9, s9, 4
	s_and_b32 s9, s9, 0x380
	v_lshrrev_b32_e32 v99, 3, v98
	v_lshlrev_b32_e32 v98, 3, v98
	v_add_u32_e32 v99, s9, v99
	v_and_b32_e32 v98, 56, v98
	v_add_u32_e32 v114, 0x8000, v0
	v_add_u32_e32 v136, 0x10000, v0
	v_lshl_or_b32 v162, v99, 10, v98
	v_add_u32_e32 v166, 0x18000, v0
	v_add_u32_e32 v174, 0x8000, v162
	v_add_u32_e32 v176, 0x10000, v162
	v_add_u32_e32 v178, 0x18000, v162
	s_setprio 1
	ds_read_b128 v[98:101], v122 offset:16384
	ds_read_b128 v[102:105], v124
	ds_read_b128 v[110:113], v122 offset:18432
	ds_read_b128 v[132:135], v122 offset:20480
	ds_read_b128 v[140:143], v122 offset:22528
	ds_read_b128 v[106:109], v124 offset:2048
	ds_read_b128 v[118:121], v124 offset:4096
	ds_read_b128 v[126:129], v124 offset:6144
	v_lshrrev_b32_e32 v14, 3, v169
	v_and_b32_e32 v15, 3, v14
	v_bfe_u32 v16, v14, 4, 1
	v_lshl_or_b32 v15, v16, 2, v15
	v_bfe_u32 v16, v14, 2, 1
	v_lshl_or_b32 v15, v16, 3, v15
	v_bfe_u32 v16, v14, 3, 1
	v_lshl_or_b32 v15, v16, 4, v15
	v_sub_u32_e32 v15, v15, v14
	v_mul_i32_i24_e32 v15, 0x400, v15
	v_and_b32_e32 v14, 7, v14
	v_lshlrev_b32_e32 v14, 3, v14
	v_xor_b32_e32 v0, v0, v14
	v_add_u32_e32 v162, v162, v15
	v_xor_b32_e32 v162, v162, v14
	v_xor_b32_e32 v114, v114, v14
	v_add_u32_e32 v174, v174, v15
	v_xor_b32_e32 v174, v174, v14
	v_xor_b32_e32 v136, v136, v14
	v_add_u32_e32 v176, v176, v15
	v_xor_b32_e32 v176, v176, v14
	v_xor_b32_e32 v166, v166, v14
	v_add_u32_e32 v178, v178, v15
	v_xor_b32_e32 v178, v178, v14
	v_readlane_b32 s14, v254, 45
	v_readlane_b32 s15, v254, 46
	v_mov_b32_e32 v163, v1
	v_mov_b32_e32 v115, v1
	v_mov_b32_e32 v175, v1
	v_mov_b32_e32 v137, v1
	v_mov_b32_e32 v177, v1
	v_mov_b32_e32 v167, v1
	v_mov_b32_e32 v179, v1
	v_lshl_add_u64 v[180:181], v[0:1], 1, s[14:15]
	v_lshl_add_u64 v[186:187], v[162:163], 1, s[34:35]
	v_lshl_add_u64 v[188:189], v[114:115], 1, s[14:15]
	v_lshl_add_u64 v[174:175], v[174:175], 1, s[34:35]
	v_lshl_add_u64 v[136:137], v[136:137], 1, s[14:15]
	v_lshl_add_u64 v[176:177], v[176:177], 1, s[34:35]
	v_lshl_add_u64 v[166:167], v[166:167], 1, s[14:15]
	v_lshl_add_u64 v[178:179], v[178:179], 1, s[34:35]
	s_add_u32 m0, s100, 0x8000
	s_waitcnt lgkmcnt(6)
	v_mfma_f32_16x16x32_bf16 v[144:147], v[98:101], v[102:105], v[34:37]
	global_load_lds_dwordx4 v2, s[98:99]
	s_waitcnt lgkmcnt(5)
	v_mfma_f32_16x16x32_bf16 v[94:97], v[110:113], v[102:105], v[94:97]
	ds_read_b128 v[148:151], v123
	s_add_u32 m0, s100, 0xc000
	s_waitcnt lgkmcnt(5)
	v_mfma_f32_16x16x32_bf16 v[158:161], v[132:135], v[102:105], v[38:41]
	global_load_lds_dwordx4 v3, s[98:99]
	s_waitcnt lgkmcnt(4)
	v_mfma_f32_16x16x32_bf16 v[90:93], v[140:143], v[102:105], v[90:93]
	ds_read_b128 v[102:105], v123 offset:2048
	s_add_u32 m0, s100, 0x9000
	s_waitcnt lgkmcnt(4)
	v_mfma_f32_16x16x32_bf16 v[162:165], v[98:101], v[106:109], v[42:45]
	global_load_lds_dwordx4 v4, s[98:99]
	v_mfma_f32_16x16x32_bf16 v[86:89], v[110:113], v[106:109], v[86:89]
	ds_read_b128 v[194:197], v123 offset:4096
	s_add_u32 m0, s100, 0xd000
	v_mfma_f32_16x16x32_bf16 v[198:201], v[132:135], v[106:109], v[46:49]
	global_load_lds_dwordx4 v5, s[98:99]
	v_mfma_f32_16x16x32_bf16 v[82:85], v[140:143], v[106:109], v[82:85]
	ds_read_b128 v[106:109], v123 offset:6144
	s_add_u32 m0, s100, 0xa000
	s_waitcnt lgkmcnt(5)
	v_mfma_f32_16x16x32_bf16 v[202:205], v[98:101], v[118:121], v[50:53]
	global_load_lds_dwordx4 v6, s[98:99]
	v_mfma_f32_16x16x32_bf16 v[78:81], v[110:113], v[118:121], v[78:81]
	ds_read_b128 v[206:209], v130 offset:16384
	s_add_u32 m0, s100, 0xe000
	v_mfma_f32_16x16x32_bf16 v[210:213], v[132:135], v[118:121], v[54:57]
	global_load_lds_dwordx4 v7, s[98:99]
	v_mfma_f32_16x16x32_bf16 v[70:73], v[140:143], v[118:121], v[70:73]
	ds_read_b128 v[118:121], v130 offset:18432
	s_add_u32 m0, s100, 0xb000
	s_waitcnt lgkmcnt(6)
	v_mfma_f32_16x16x32_bf16 v[98:101], v[98:101], v[126:129], v[58:61]
	global_load_lds_dwordx4 v8, s[98:99]
	v_mfma_f32_16x16x32_bf16 v[66:69], v[110:113], v[126:129], v[66:69]
	ds_read_b128 v[110:113], v130 offset:20480
	s_add_u32 m0, s100, 0xf000
	v_mfma_f32_16x16x32_bf16 v[132:135], v[132:135], v[126:129], v[62:65]
	global_load_lds_dwordx4 v9, s[98:99]
	v_mfma_f32_16x16x32_bf16 v[74:77], v[140:143], v[126:129], v[74:77]
	ds_read_b128 v[126:129], v130 offset:22528
	s_waitcnt lgkmcnt(3)
	v_mfma_f32_16x16x32_bf16 v[140:143], v[206:209], v[148:151], v[144:147]
	s_waitcnt lgkmcnt(2)
	v_mfma_f32_16x16x32_bf16 v[94:97], v[118:121], v[148:151], v[94:97]
	s_waitcnt lgkmcnt(1)
	v_mfma_f32_16x16x32_bf16 v[144:147], v[110:113], v[148:151], v[158:161]
	s_waitcnt lgkmcnt(0)
	v_mfma_f32_16x16x32_bf16 v[90:93], v[126:129], v[148:151], v[90:93]
	v_mfma_f32_16x16x32_bf16 v[148:151], v[206:209], v[102:105], v[162:165]
	v_mfma_f32_16x16x32_bf16 v[86:89], v[118:121], v[102:105], v[86:89]
	v_mfma_f32_16x16x32_bf16 v[158:161], v[110:113], v[102:105], v[198:201]
	v_mfma_f32_16x16x32_bf16 v[82:85], v[126:129], v[102:105], v[82:85]
	v_mfma_f32_16x16x32_bf16 v[102:105], v[206:209], v[194:197], v[202:205]
	v_mfma_f32_16x16x32_bf16 v[78:81], v[118:121], v[194:197], v[78:81]
	v_mfma_f32_16x16x32_bf16 v[162:165], v[110:113], v[194:197], v[210:213]
	v_mfma_f32_16x16x32_bf16 v[70:73], v[126:129], v[194:197], v[70:73]
	v_mfma_f32_16x16x32_bf16 v[98:101], v[206:209], v[106:109], v[98:101]
	v_mfma_f32_16x16x32_bf16 v[66:69], v[118:121], v[106:109], v[66:69]
	v_mfma_f32_16x16x32_bf16 v[110:113], v[110:113], v[106:109], v[132:135]
	v_mfma_f32_16x16x32_bf16 v[74:77], v[126:129], v[106:109], v[74:77]
	s_waitcnt vmcnt(0)
	s_setprio 0
	s_waitcnt lgkmcnt(0)
	s_barrier
	s_setprio 1
	ds_read_b128 v[26:29], v122 offset:49152
	ds_read_b128 v[10:13], v124 offset:32768
	ds_read_b128 v[18:21], v124 offset:34816
	ds_read_b128 v[30:33], v122 offset:51200
	ds_read_b128 v[106:109], v124 offset:36864
	ds_read_b128 v[114:117], v124 offset:38912
	ds_read_b128 v[118:121], v122 offset:53248
	ds_read_b128 v[124:127], v122 offset:55296
	s_add_u32 m0, s100, 0x0
	s_waitcnt lgkmcnt(6)
	v_mfma_f32_16x16x32_bf16 v[132:135], v[26:29], v[10:13], v[140:143]
	global_load_lds_dwordx4 v[180:181], off
	s_waitcnt lgkmcnt(4)
	v_mfma_f32_16x16x32_bf16 v[94:97], v[30:33], v[10:13], v[94:97]
	ds_read_b128 v[140:143], v123 offset:32768
	s_add_u32 m0, s100, 0x4000
	s_waitcnt lgkmcnt(2)
	v_mfma_f32_16x16x32_bf16 v[144:147], v[118:121], v[10:13], v[144:147]
	global_load_lds_dwordx4 v[186:187], off
	s_waitcnt lgkmcnt(1)
	v_mfma_f32_16x16x32_bf16 v[90:93], v[124:127], v[10:13], v[90:93]
	ds_read_b128 v[194:197], v123 offset:34816
	s_add_u32 m0, s100, 0x1000
	v_mfma_f32_16x16x32_bf16 v[148:151], v[26:29], v[18:21], v[148:151]
	global_load_lds_dwordx4 v[188:189], off
	v_mfma_f32_16x16x32_bf16 v[86:89], v[30:33], v[18:21], v[86:89]
	ds_read_b128 v[198:201], v123 offset:36864
	s_add_u32 m0, s100, 0x5000
	v_mfma_f32_16x16x32_bf16 v[158:161], v[118:121], v[18:21], v[158:161]
	global_load_lds_dwordx4 v[174:175], off
	v_mfma_f32_16x16x32_bf16 v[82:85], v[124:127], v[18:21], v[82:85]
	ds_read_b128 v[202:205], v123 offset:38912
	s_add_u32 m0, s100, 0x2000
	v_mfma_f32_16x16x32_bf16 v[206:209], v[26:29], v[106:109], v[102:105]
	global_load_lds_dwordx4 v[136:137], off
	v_mfma_f32_16x16x32_bf16 v[78:81], v[30:33], v[106:109], v[78:81]
	ds_read_b128 v[210:213], v130 offset:49152
	s_add_u32 m0, s100, 0x6000
	v_mfma_f32_16x16x32_bf16 v[162:165], v[118:121], v[106:109], v[162:165]
	global_load_lds_dwordx4 v[176:177], off
	v_mfma_f32_16x16x32_bf16 v[70:73], v[124:127], v[106:109], v[70:73]
	ds_read_b128 v[214:217], v130 offset:51200
	s_add_u32 m0, s100, 0x3000
	v_mfma_f32_16x16x32_bf16 v[218:221], v[26:29], v[114:117], v[98:101]
	global_load_lds_dwordx4 v[166:167], off
	v_mfma_f32_16x16x32_bf16 v[66:69], v[30:33], v[114:117], v[66:69]
	ds_read_b128 v[222:225], v130 offset:53248
	s_add_u32 m0, s100, 0x7000
	v_mfma_f32_16x16x32_bf16 v[226:229], v[118:121], v[114:117], v[110:113]
	global_load_lds_dwordx4 v[178:179], off
	v_mfma_f32_16x16x32_bf16 v[230:233], v[124:127], v[114:117], v[74:77]
	s_waitcnt lgkmcnt(2)
	v_mfma_f32_16x16x32_bf16 v[126:129], v[210:213], v[140:143], v[132:135]
	ds_read_b128 v[130:133], v130 offset:55296
	s_waitcnt lgkmcnt(2)
	v_mfma_f32_16x16x32_bf16 v[122:125], v[214:217], v[140:143], v[94:97]
	s_waitcnt lgkmcnt(1)
	v_mfma_f32_16x16x32_bf16 v[118:121], v[222:225], v[140:143], v[144:147]
	s_waitcnt lgkmcnt(0)
	v_mfma_f32_16x16x32_bf16 v[114:117], v[130:133], v[140:143], v[90:93]
	v_mfma_f32_16x16x32_bf16 v[110:113], v[210:213], v[194:197], v[148:151]
	v_mfma_f32_16x16x32_bf16 v[106:109], v[214:217], v[194:197], v[86:89]
	v_mfma_f32_16x16x32_bf16 v[102:105], v[222:225], v[194:197], v[158:161]
	v_mfma_f32_16x16x32_bf16 v[98:101], v[130:133], v[194:197], v[82:85]
	v_mfma_f32_16x16x32_bf16 v[94:97], v[210:213], v[198:201], v[206:209]
	v_mfma_f32_16x16x32_bf16 v[90:93], v[214:217], v[198:201], v[78:81]
	v_mfma_f32_16x16x32_bf16 v[86:89], v[222:225], v[198:201], v[162:165]
	v_mfma_f32_16x16x32_bf16 v[82:85], v[130:133], v[198:201], v[70:73]
	v_mfma_f32_16x16x32_bf16 v[78:81], v[210:213], v[202:205], v[218:221]
	v_mfma_f32_16x16x32_bf16 v[74:77], v[214:217], v[202:205], v[66:69]
	v_mfma_f32_16x16x32_bf16 v[70:73], v[222:225], v[202:205], v[226:229]
	v_mfma_f32_16x16x32_bf16 v[66:69], v[130:133], v[202:205], v[230:233]
	s_setprio 0
	v_add_u32_e32 v134, s4, v152
	v_ashrrev_i32_e32 v135, 31, v134
	v_lshlrev_b64 v[136:137], 12, v[134:135]
	v_or_b32_e32 v140, s10, v153
	v_mov_b32_e32 v141, v1
	v_cndmask_b32_e64 v0, 0, 1, s[42:43]
	v_lshl_add_u64 v[130:131], s[40:41], 0, v[136:137]
	v_cmp_ne_u32_e64 s[38:39], 1, v0
	s_andn2_b64 vcc, exec, s[42:43]
	v_lshl_add_u64 v[146:147], v[140:141], 2, v[130:131]
	s_barrier
	s_cbranch_vccnz .LBB0_160
	global_load_dwordx4 v[130:133], v[146:147], off
	s_mov_b64 s[46:47], 0
	s_branch .LBB0_161

.LBB0_475:
	s_setprio 1
	s_add_u32 s98, s28, 0x80
	s_addc_u32 s99, s29, 0
	v_add_u32_e32 v120, v117, v116
	v_add_u32_e32 v122, v117, v118
	v_add_u32_e32 v121, v119, v118
	ds_read_b128 v[124:127], v120 offset:16384
	ds_read_b128 v[144:147], v120 offset:18432
	ds_read_b128 v[156:159], v120 offset:20480
	ds_read_b128 v[160:163], v120 offset:22528
	ds_read_b128 v[128:131], v122
	ds_read_b128 v[132:135], v122 offset:2048
	ds_read_b128 v[148:151], v122 offset:4096
	ds_read_b128 v[152:155], v122 offset:6144
	s_add_u32 m0, s100, 0x8000
	s_waitcnt lgkmcnt(3)
	v_mfma_f32_16x16x32_bf16 v[34:37], v[124:127], v[128:131], v[34:37]
	global_load_lds_dwordx4 v164, s[98:99]
	v_mfma_f32_16x16x32_bf16 v[94:97], v[144:147], v[128:131], v[94:97]
	ds_read_b128 v[194:197], v121
	s_add_u32 m0, s100, 0xc000
	v_mfma_f32_16x16x32_bf16 v[38:41], v[156:159], v[128:131], v[38:41]
	global_load_lds_dwordx4 v165, s[98:99]
	v_mfma_f32_16x16x32_bf16 v[90:93], v[160:163], v[128:131], v[90:93]
	v_add_u32_e32 v130, v119, v116
	ds_read_b128 v[202:205], v121 offset:2048
	s_add_u32 m0, s100, 0x9000
	s_waitcnt lgkmcnt(4)
	v_mfma_f32_16x16x32_bf16 v[42:45], v[124:127], v[132:135], v[42:45]
	global_load_lds_dwordx4 v166, s[98:99]
	v_mfma_f32_16x16x32_bf16 v[86:89], v[144:147], v[132:135], v[86:89]
	ds_read_b128 v[210:213], v121 offset:4096
	s_add_u32 m0, s100, 0xd000
	v_mfma_f32_16x16x32_bf16 v[46:49], v[156:159], v[132:135], v[46:49]
	global_load_lds_dwordx4 v167, s[98:99]
	v_mfma_f32_16x16x32_bf16 v[82:85], v[160:163], v[132:135], v[82:85]
	ds_read_b128 v[132:135], v121 offset:6144
	s_add_u32 m0, s100, 0xa000
	s_waitcnt lgkmcnt(5)
	v_mfma_f32_16x16x32_bf16 v[50:53], v[124:127], v[148:151], v[50:53]
	global_load_lds_dwordx4 v198, s[98:99]
	v_mfma_f32_16x16x32_bf16 v[78:81], v[144:147], v[148:151], v[78:81]
	ds_read_b128 v[222:225], v130 offset:16384
	s_add_u32 m0, s100, 0xe000
	v_mfma_f32_16x16x32_bf16 v[54:57], v[156:159], v[148:151], v[54:57]
	global_load_lds_dwordx4 v199, s[98:99]
	v_mfma_f32_16x16x32_bf16 v[70:73], v[160:163], v[148:151], v[70:73]
	ds_read_b128 v[148:151], v130 offset:18432
	s_add_u32 m0, s100, 0xb000
	s_waitcnt lgkmcnt(6)
	v_mfma_f32_16x16x32_bf16 v[58:61], v[124:127], v[152:155], v[58:61]
	global_load_lds_dwordx4 v200, s[98:99]
	v_mfma_f32_16x16x32_bf16 v[66:69], v[144:147], v[152:155], v[66:69]
	ds_read_b128 v[144:147], v130 offset:20480
	s_add_u32 m0, s100, 0xf000
	v_mfma_f32_16x16x32_bf16 v[62:65], v[156:159], v[152:155], v[62:65]
	global_load_lds_dwordx4 v201, s[98:99]
	v_mfma_f32_16x16x32_bf16 v[74:77], v[160:163], v[152:155], v[74:77]
	ds_read_b128 v[152:155], v130 offset:22528
	s_waitcnt lgkmcnt(3)
	v_mfma_f32_16x16x32_bf16 v[34:37], v[222:225], v[194:197], v[34:37]
	s_waitcnt lgkmcnt(2)
	v_mfma_f32_16x16x32_bf16 v[94:97], v[148:151], v[194:197], v[94:97]
	s_waitcnt lgkmcnt(1)
	v_mfma_f32_16x16x32_bf16 v[38:41], v[144:147], v[194:197], v[38:41]
	s_waitcnt lgkmcnt(0)
	v_mfma_f32_16x16x32_bf16 v[90:93], v[152:155], v[194:197], v[90:93]
	v_mfma_f32_16x16x32_bf16 v[42:45], v[222:225], v[202:205], v[42:45]
	v_mfma_f32_16x16x32_bf16 v[86:89], v[148:151], v[202:205], v[86:89]
	v_mfma_f32_16x16x32_bf16 v[46:49], v[144:147], v[202:205], v[46:49]
	v_mfma_f32_16x16x32_bf16 v[82:85], v[152:155], v[202:205], v[82:85]
	v_mfma_f32_16x16x32_bf16 v[50:53], v[222:225], v[210:213], v[50:53]
	v_mfma_f32_16x16x32_bf16 v[78:81], v[148:151], v[210:213], v[78:81]
	v_mfma_f32_16x16x32_bf16 v[54:57], v[144:147], v[210:213], v[54:57]
	v_mfma_f32_16x16x32_bf16 v[70:73], v[152:155], v[210:213], v[70:73]
	v_mfma_f32_16x16x32_bf16 v[58:61], v[222:225], v[132:135], v[58:61]
	v_mfma_f32_16x16x32_bf16 v[66:69], v[148:151], v[132:135], v[66:69]
	v_mfma_f32_16x16x32_bf16 v[62:65], v[144:147], v[132:135], v[62:65]
	v_mfma_f32_16x16x32_bf16 v[74:77], v[152:155], v[132:135], v[74:77]
	s_waitcnt vmcnt(0)
	s_setprio 0
	s_waitcnt lgkmcnt(0)
	s_barrier
	s_setprio 1
	s_add_u32 s98, s98, 0x80
	s_addc_u32 s99, s99, 0
	ds_read_b128 v[26:29], v120 offset:49152
	ds_read_b128 v[10:13], v122 offset:32768
	ds_read_b128 v[30:33], v120 offset:51200
	ds_read_b128 v[148:151], v120 offset:53248
	ds_read_b128 v[152:155], v120 offset:55296
	ds_read_b128 v[18:21], v122 offset:34816
	ds_read_b128 v[132:135], v122 offset:36864
	ds_read_b128 v[144:147], v122 offset:38912
	s_add_u32 m0, s100, 0x0
	s_waitcnt lgkmcnt(6)
	v_mfma_f32_16x16x32_bf16 v[34:37], v[26:29], v[10:13], v[34:37]
	global_load_lds_dwordx4 v164, s[98:99]
	s_waitcnt lgkmcnt(5)
	v_mfma_f32_16x16x32_bf16 v[94:97], v[30:33], v[10:13], v[94:97]
	ds_read_b128 v[160:163], v121 offset:32768
	s_add_u32 m0, s100, 0x4000
	s_waitcnt lgkmcnt(5)
	v_mfma_f32_16x16x32_bf16 v[38:41], v[148:151], v[10:13], v[38:41]
	global_load_lds_dwordx4 v165, s[98:99]
	s_waitcnt lgkmcnt(4)
	v_mfma_f32_16x16x32_bf16 v[90:93], v[152:155], v[10:13], v[90:93]
	ds_read_b128 v[194:197], v121 offset:34816
	s_add_u32 m0, s100, 0x1000
	s_waitcnt lgkmcnt(4)
	v_mfma_f32_16x16x32_bf16 v[42:45], v[26:29], v[18:21], v[42:45]
	global_load_lds_dwordx4 v166, s[98:99]
	v_mfma_f32_16x16x32_bf16 v[86:89], v[30:33], v[18:21], v[86:89]
	ds_read_b128 v[202:205], v121 offset:36864
	s_add_u32 m0, s100, 0x5000
	v_mfma_f32_16x16x32_bf16 v[46:49], v[148:151], v[18:21], v[46:49]
	global_load_lds_dwordx4 v167, s[98:99]
	v_mfma_f32_16x16x32_bf16 v[82:85], v[152:155], v[18:21], v[82:85]
	ds_read_b128 v[210:213], v121 offset:38912
	s_add_u32 m0, s100, 0x2000
	s_waitcnt lgkmcnt(5)
	v_mfma_f32_16x16x32_bf16 v[50:53], v[26:29], v[132:135], v[50:53]
	global_load_lds_dwordx4 v198, s[98:99]
	v_mfma_f32_16x16x32_bf16 v[78:81], v[30:33], v[132:135], v[78:81]
	ds_read_b128 v[222:225], v130 offset:49152
	s_add_u32 m0, s100, 0x6000
	v_mfma_f32_16x16x32_bf16 v[54:57], v[148:151], v[132:135], v[54:57]
	global_load_lds_dwordx4 v199, s[98:99]
	v_mfma_f32_16x16x32_bf16 v[70:73], v[152:155], v[132:135], v[70:73]
	ds_read_b128 v[132:135], v130 offset:51200
	s_add_u32 m0, s100, 0x3000
	s_waitcnt lgkmcnt(6)
	v_mfma_f32_16x16x32_bf16 v[58:61], v[26:29], v[144:147], v[58:61]
	global_load_lds_dwordx4 v200, s[98:99]
	v_mfma_f32_16x16x32_bf16 v[66:69], v[30:33], v[144:147], v[66:69]
	ds_read_b128 v[230:233], v130 offset:53248
	s_add_u32 m0, s100, 0x7000
	v_mfma_f32_16x16x32_bf16 v[62:65], v[148:151], v[144:147], v[62:65]
	global_load_lds_dwordx4 v201, s[98:99]
	v_mfma_f32_16x16x32_bf16 v[74:77], v[152:155], v[144:147], v[74:77]
	ds_read_b128 v[144:147], v130 offset:55296
	s_waitcnt lgkmcnt(3)
	v_mfma_f32_16x16x32_bf16 v[34:37], v[222:225], v[160:163], v[34:37]
	s_waitcnt lgkmcnt(2)
	v_mfma_f32_16x16x32_bf16 v[94:97], v[132:135], v[160:163], v[94:97]
	s_waitcnt lgkmcnt(1)
	v_mfma_f32_16x16x32_bf16 v[38:41], v[230:233], v[160:163], v[38:41]
	s_waitcnt lgkmcnt(0)
	v_mfma_f32_16x16x32_bf16 v[90:93], v[144:147], v[160:163], v[90:93]
	v_mfma_f32_16x16x32_bf16 v[42:45], v[222:225], v[194:197], v[42:45]
	v_mfma_f32_16x16x32_bf16 v[86:89], v[132:135], v[194:197], v[86:89]
	v_mfma_f32_16x16x32_bf16 v[46:49], v[230:233], v[194:197], v[46:49]
	v_mfma_f32_16x16x32_bf16 v[82:85], v[144:147], v[194:197], v[82:85]
	v_mfma_f32_16x16x32_bf16 v[50:53], v[222:225], v[202:205], v[50:53]
	v_mfma_f32_16x16x32_bf16 v[78:81], v[132:135], v[202:205], v[78:81]
	v_mfma_f32_16x16x32_bf16 v[54:57], v[230:233], v[202:205], v[54:57]
	v_mfma_f32_16x16x32_bf16 v[70:73], v[144:147], v[202:205], v[70:73]
	v_mfma_f32_16x16x32_bf16 v[58:61], v[222:225], v[210:213], v[58:61]
	v_mfma_f32_16x16x32_bf16 v[66:69], v[132:135], v[210:213], v[66:69]
	v_mfma_f32_16x16x32_bf16 v[62:65], v[230:233], v[210:213], v[62:65]
	v_mfma_f32_16x16x32_bf16 v[74:77], v[144:147], v[210:213], v[74:77]
	s_waitcnt vmcnt(0)
	s_setprio 0
	s_add_i32 s8, s8, 2
	s_add_u32 s28, s28, 0x100
	s_addc_u32 s29, s29, 0
	s_cmp_lt_u32 s8, 12
	s_waitcnt lgkmcnt(0)
	s_barrier
	s_cbranch_scc1 .LBB0_475
	v_mov_b32_e32 v2, v164
	v_mov_b32_e32 v3, v165
	v_mov_b32_e32 v4, v166
	v_mov_b32_e32 v5, v167
	v_mov_b32_e32 v6, v198
	v_mov_b32_e32 v7, v199
	v_mov_b32_e32 v8, v200
	v_mov_b32_e32 v9, v201
	s_add_u32 s98, s28, 0x80
	s_addc_u32 s99, s29, 0
	s_add_i32 s8, s11, s2
	s_cmpk_lt_u32 s8, 0x420
	s_cselect_b64 s[56:57], -1, 0
	s_and_b64 s[14:15], s[56:57], exec
	s_cselect_b32 s10, s8, s11
	s_mul_hi_u32 s11, s10, 0x3e0f83e1
	s_lshr_b32 s11, s11, 6
	s_mul_i32 s14, s11, 0x108
	v_mov_b32_e32 v0, v169
	s_sub_i32 s10, s10, s14
	s_lshl_b32 s11, s11, 3
	s_add_i32 s11, s11, s21
	s_and_b32 s14, s10, 7
	v_lshlrev_b32_e32 v98, 3, v0
	v_lshlrev_b32_e32 v0, 7, v0
	s_or_b32 s11, s11, s14
	v_and_b32_e32 v0, 0xfffffc00, v0
	v_lshl_add_u32 v0, s11, 17, v0
	v_and_or_b32 v0, v98, 56, v0
	v_mov_b32_e32 v98, v169
	s_lshl_b32 s10, s10, 4
	s_and_b32 s10, s10, 0x1f80
	v_lshrrev_b32_e32 v99, 3, v98
	v_lshlrev_b32_e32 v98, 3, v98
	v_add_u32_e32 v99, s10, v99
	v_and_b32_e32 v98, 56, v98
	v_add_u32_e32 v128, 0x8000, v0
	v_add_u32_e32 v136, 0x10000, v0
	v_lshl_or_b32 v160, v99, 10, v98
	v_add_u32_e32 v210, 0x18000, v0
	v_add_u32_e32 v198, 0x8000, v160
	v_add_u32_e32 v212, 0x10000, v160
	v_add_u32_e32 v214, 0x18000, v160
	s_setprio 1
	ds_read_b128 v[98:101], v120 offset:16384
	ds_read_b128 v[102:105], v122
	ds_read_b128 v[110:113], v120 offset:18432
	ds_read_b128 v[132:135], v120 offset:20480
	ds_read_b128 v[144:147], v120 offset:22528
	ds_read_b128 v[106:109], v122 offset:2048
	ds_read_b128 v[116:119], v122 offset:4096
	ds_read_b128 v[124:127], v122 offset:6144
	v_lshrrev_b32_e32 v14, 3, v169
	v_and_b32_e32 v15, 3, v14
	v_bfe_u32 v16, v14, 4, 1
	v_lshl_or_b32 v15, v16, 2, v15
	v_bfe_u32 v16, v14, 2, 1
	v_lshl_or_b32 v15, v16, 3, v15
	v_bfe_u32 v16, v14, 3, 1
	v_lshl_or_b32 v15, v16, 4, v15
	v_sub_u32_e32 v15, v15, v14
	v_mul_i32_i24_e32 v15, 0x400, v15
	v_and_b32_e32 v14, 7, v14
	v_lshlrev_b32_e32 v14, 3, v14
	v_xor_b32_e32 v0, v0, v14
	v_add_u32_e32 v160, v160, v15
	v_xor_b32_e32 v160, v160, v14
	v_xor_b32_e32 v128, v128, v14
	v_add_u32_e32 v198, v198, v15
	v_xor_b32_e32 v198, v198, v14
	v_xor_b32_e32 v136, v136, v14
	v_add_u32_e32 v212, v212, v15
	v_xor_b32_e32 v212, v212, v14
	v_xor_b32_e32 v210, v210, v14
	v_add_u32_e32 v214, v214, v15
	v_xor_b32_e32 v214, v214, v14
	v_mov_b32_e32 v161, v1
	v_mov_b32_e32 v129, v1
	v_mov_b32_e32 v199, v1
	v_mov_b32_e32 v137, v1
	v_mov_b32_e32 v213, v1
	v_mov_b32_e32 v211, v1
	v_mov_b32_e32 v215, v1
	v_lshl_add_u64 v[216:217], v[0:1], 1, s[48:49]
	v_lshl_add_u64 v[218:219], v[160:161], 1, s[50:51]
	v_lshl_add_u64 v[220:221], v[128:129], 1, s[48:49]
	v_lshl_add_u64 v[222:223], v[198:199], 1, s[50:51]
	v_lshl_add_u64 v[136:137], v[136:137], 1, s[48:49]
	v_lshl_add_u64 v[212:213], v[212:213], 1, s[50:51]
	v_lshl_add_u64 v[224:225], v[210:211], 1, s[48:49]
	v_lshl_add_u64 v[226:227], v[214:215], 1, s[50:51]
	s_add_u32 m0, s100, 0x8000
	s_waitcnt lgkmcnt(6)
	v_mfma_f32_16x16x32_bf16 v[148:151], v[98:101], v[102:105], v[34:37]
	global_load_lds_dwordx4 v2, s[98:99]
	s_waitcnt lgkmcnt(5)
	v_mfma_f32_16x16x32_bf16 v[94:97], v[110:113], v[102:105], v[94:97]
	ds_read_b128 v[152:155], v121
	s_add_u32 m0, s100, 0xc000
	s_waitcnt lgkmcnt(5)
	v_mfma_f32_16x16x32_bf16 v[156:159], v[132:135], v[102:105], v[38:41]
	global_load_lds_dwordx4 v3, s[98:99]
	s_waitcnt lgkmcnt(4)
	v_mfma_f32_16x16x32_bf16 v[90:93], v[144:147], v[102:105], v[90:93]
	ds_read_b128 v[102:105], v121 offset:2048
	s_add_u32 m0, s100, 0x9000
	s_waitcnt lgkmcnt(4)
	v_mfma_f32_16x16x32_bf16 v[160:163], v[98:101], v[106:109], v[42:45]
	global_load_lds_dwordx4 v4, s[98:99]
	v_mfma_f32_16x16x32_bf16 v[86:89], v[110:113], v[106:109], v[86:89]
	ds_read_b128 v[164:167], v121 offset:4096
	s_add_u32 m0, s100, 0xd000
	v_mfma_f32_16x16x32_bf16 v[194:197], v[132:135], v[106:109], v[46:49]
	global_load_lds_dwordx4 v5, s[98:99]
	v_mfma_f32_16x16x32_bf16 v[82:85], v[144:147], v[106:109], v[82:85]
	ds_read_b128 v[106:109], v121 offset:6144
	s_add_u32 m0, s100, 0xa000
	s_waitcnt lgkmcnt(5)
	v_mfma_f32_16x16x32_bf16 v[198:201], v[98:101], v[116:119], v[50:53]
	global_load_lds_dwordx4 v6, s[98:99]
	v_mfma_f32_16x16x32_bf16 v[78:81], v[110:113], v[116:119], v[78:81]
	ds_read_b128 v[202:205], v130 offset:16384
	s_add_u32 m0, s100, 0xe000
	v_mfma_f32_16x16x32_bf16 v[206:209], v[132:135], v[116:119], v[54:57]
	global_load_lds_dwordx4 v7, s[98:99]
	v_mfma_f32_16x16x32_bf16 v[70:73], v[144:147], v[116:119], v[70:73]
	ds_read_b128 v[116:119], v130 offset:18432
	s_add_u32 m0, s100, 0xb000
	s_waitcnt lgkmcnt(6)
	v_mfma_f32_16x16x32_bf16 v[98:101], v[98:101], v[124:127], v[58:61]
	global_load_lds_dwordx4 v8, s[98:99]
	v_mfma_f32_16x16x32_bf16 v[66:69], v[110:113], v[124:127], v[66:69]
	ds_read_b128 v[110:113], v130 offset:20480
	s_add_u32 m0, s100, 0xf000
	v_mfma_f32_16x16x32_bf16 v[132:135], v[132:135], v[124:127], v[62:65]
	global_load_lds_dwordx4 v9, s[98:99]
	v_mfma_f32_16x16x32_bf16 v[74:77], v[144:147], v[124:127], v[74:77]
	ds_read_b128 v[124:127], v130 offset:22528
	s_waitcnt lgkmcnt(3)
	v_mfma_f32_16x16x32_bf16 v[144:147], v[202:205], v[152:155], v[148:151]
	s_waitcnt lgkmcnt(2)
	v_mfma_f32_16x16x32_bf16 v[94:97], v[116:119], v[152:155], v[94:97]
	s_waitcnt lgkmcnt(1)
	v_mfma_f32_16x16x32_bf16 v[148:151], v[110:113], v[152:155], v[156:159]
	s_waitcnt lgkmcnt(0)
	v_mfma_f32_16x16x32_bf16 v[90:93], v[124:127], v[152:155], v[90:93]
	v_mfma_f32_16x16x32_bf16 v[152:155], v[202:205], v[102:105], v[160:163]
	v_mfma_f32_16x16x32_bf16 v[86:89], v[116:119], v[102:105], v[86:89]
	v_mfma_f32_16x16x32_bf16 v[156:159], v[110:113], v[102:105], v[194:197]
	v_mfma_f32_16x16x32_bf16 v[82:85], v[124:127], v[102:105], v[82:85]
	v_mfma_f32_16x16x32_bf16 v[102:105], v[202:205], v[164:167], v[198:201]
	v_mfma_f32_16x16x32_bf16 v[78:81], v[116:119], v[164:167], v[78:81]
	v_mfma_f32_16x16x32_bf16 v[160:163], v[110:113], v[164:167], v[206:209]
	v_mfma_f32_16x16x32_bf16 v[70:73], v[124:127], v[164:167], v[70:73]
	v_mfma_f32_16x16x32_bf16 v[98:101], v[202:205], v[106:109], v[98:101]
	v_mfma_f32_16x16x32_bf16 v[66:69], v[116:119], v[106:109], v[66:69]
	v_mfma_f32_16x16x32_bf16 v[110:113], v[110:113], v[106:109], v[132:135]
	v_mfma_f32_16x16x32_bf16 v[74:77], v[124:127], v[106:109], v[74:77]
	s_waitcnt vmcnt(0)
	s_setprio 0
	s_waitcnt lgkmcnt(0)
	s_barrier
	s_setprio 1
	ds_read_b128 v[26:29], v120 offset:49152
	ds_read_b128 v[10:13], v122 offset:32768
	ds_read_b128 v[18:21], v122 offset:34816
	ds_read_b128 v[30:33], v120 offset:51200
	ds_read_b128 v[106:109], v122 offset:36864
	ds_read_b128 v[114:117], v122 offset:38912
	ds_read_b128 v[122:125], v120 offset:53248
	ds_read_b128 v[126:129], v120 offset:55296
	s_add_u32 m0, s100, 0x0
	s_waitcnt lgkmcnt(6)
	v_mfma_f32_16x16x32_bf16 v[132:135], v[26:29], v[10:13], v[144:147]
	global_load_lds_dwordx4 v[216:217], off
	s_waitcnt lgkmcnt(4)
	v_mfma_f32_16x16x32_bf16 v[94:97], v[30:33], v[10:13], v[94:97]
	ds_read_b128 v[144:147], v121 offset:32768
	s_add_u32 m0, s100, 0x4000
	s_waitcnt lgkmcnt(2)
	v_mfma_f32_16x16x32_bf16 v[148:151], v[122:125], v[10:13], v[148:151]
	global_load_lds_dwordx4 v[218:219], off
	s_waitcnt lgkmcnt(1)
	v_mfma_f32_16x16x32_bf16 v[90:93], v[126:129], v[10:13], v[90:93]
	ds_read_b128 v[164:167], v121 offset:34816
	s_add_u32 m0, s100, 0x1000
	v_mfma_f32_16x16x32_bf16 v[152:155], v[26:29], v[18:21], v[152:155]
	global_load_lds_dwordx4 v[220:221], off
	v_mfma_f32_16x16x32_bf16 v[86:89], v[30:33], v[18:21], v[86:89]
	ds_read_b128 v[194:197], v121 offset:36864
	s_add_u32 m0, s100, 0x5000
	v_mfma_f32_16x16x32_bf16 v[156:159], v[122:125], v[18:21], v[156:159]
	global_load_lds_dwordx4 v[222:223], off
	v_mfma_f32_16x16x32_bf16 v[82:85], v[126:129], v[18:21], v[82:85]
	ds_read_b128 v[198:201], v121 offset:38912
	s_add_u32 m0, s100, 0x2000
	v_mfma_f32_16x16x32_bf16 v[202:205], v[26:29], v[106:109], v[102:105]
	global_load_lds_dwordx4 v[136:137], off
	v_mfma_f32_16x16x32_bf16 v[78:81], v[30:33], v[106:109], v[78:81]
	ds_read_b128 v[206:209], v130 offset:49152
	s_add_u32 m0, s100, 0x6000
	v_mfma_f32_16x16x32_bf16 v[160:163], v[122:125], v[106:109], v[160:163]
	global_load_lds_dwordx4 v[212:213], off
	v_mfma_f32_16x16x32_bf16 v[70:73], v[126:129], v[106:109], v[70:73]
	ds_read_b128 v[210:213], v130 offset:51200
	s_add_u32 m0, s100, 0x3000
	v_mfma_f32_16x16x32_bf16 v[214:217], v[26:29], v[114:117], v[98:101]
	global_load_lds_dwordx4 v[224:225], off
	v_mfma_f32_16x16x32_bf16 v[66:69], v[30:33], v[114:117], v[66:69]
	ds_read_b128 v[218:221], v130 offset:53248
	s_add_u32 m0, s100, 0x7000
	v_mfma_f32_16x16x32_bf16 v[222:225], v[122:125], v[114:117], v[110:113]
	global_load_lds_dwordx4 v[226:227], off
	v_mfma_f32_16x16x32_bf16 v[226:229], v[126:129], v[114:117], v[74:77]
	s_waitcnt lgkmcnt(2)
	v_mfma_f32_16x16x32_bf16 v[126:129], v[206:209], v[144:147], v[132:135]
	ds_read_b128 v[130:133], v130 offset:55296
	s_waitcnt lgkmcnt(2)
	v_mfma_f32_16x16x32_bf16 v[122:125], v[210:213], v[144:147], v[94:97]
	s_waitcnt lgkmcnt(1)
	v_mfma_f32_16x16x32_bf16 v[118:121], v[218:221], v[144:147], v[148:151]
	s_waitcnt lgkmcnt(0)
	v_mfma_f32_16x16x32_bf16 v[114:117], v[130:133], v[144:147], v[90:93]
	v_mfma_f32_16x16x32_bf16 v[110:113], v[206:209], v[164:167], v[152:155]
	v_mfma_f32_16x16x32_bf16 v[106:109], v[210:213], v[164:167], v[86:89]
	v_mfma_f32_16x16x32_bf16 v[102:105], v[218:221], v[164:167], v[156:159]
	v_mfma_f32_16x16x32_bf16 v[98:101], v[130:133], v[164:167], v[82:85]
	v_mfma_f32_16x16x32_bf16 v[94:97], v[206:209], v[194:197], v[202:205]
	v_mfma_f32_16x16x32_bf16 v[90:93], v[210:213], v[194:197], v[78:81]
	v_mfma_f32_16x16x32_bf16 v[86:89], v[218:221], v[194:197], v[160:163]
	v_mfma_f32_16x16x32_bf16 v[82:85], v[130:133], v[194:197], v[70:73]
	v_mfma_f32_16x16x32_bf16 v[74:77], v[206:209], v[198:201], v[214:217]
	v_mfma_f32_16x16x32_bf16 v[70:73], v[210:213], v[198:201], v[66:69]
	v_mfma_f32_16x16x32_bf16 v[66:69], v[218:221], v[198:201], v[222:225]
	v_mfma_f32_16x16x32_bf16 v[78:81], v[130:133], v[198:201], v[226:229]
	s_setprio 0
	s_cmpk_gt_u32 s16, 0x9ff
	s_cselect_b64 s[42:43], -1, 0
	s_and_b32 s17, s16, 0x1f00
	s_cmpk_eq_i32 s17, 0xe00
	s_cselect_b64 s[40:41], -1, 0
	s_cmpk_gt_u32 s16, 0x5ff
	s_cselect_b64 s[46:47], -1, 0
	s_cmpk_gt_u32 s16, 0xbff
	s_cselect_b64 s[62:63], -1, 0
	s_cmpk_lt_u32 s16, 0xd00
	s_cselect_b64 s[14:15], -1, 0
	s_and_b64 s[26:27], s[14:15], exec
	s_movk_i32 s21, 0xf300
	s_cselect_b32 s28, 0xfffff400, s21
	s_nor_b64 s[60:61], s[14:15], s[40:41]
	s_cmpk_gt_u32 s16, 0xfff
	s_cselect_b64 s[58:59], -1, 0
	s_cmpk_lt_u32 s16, 0xe00
	v_add_u32_e32 v0, s9, v141
	s_cselect_b64 s[14:15], -1, 0
	v_or_b32_e32 v136, v0, v140
	s_movk_i32 s21, 0xc0
	s_and_b64 s[14:15], s[14:15], exec
	v_mad_i64_i32 v[134:135], s[26:27], v136, s21, 0
	s_movk_i32 s21, 0x1fcf
	s_movk_i32 s14, 0xf100
	v_bitop3_b32 v144, v0, s21, v140 bitop3:0xc8
	v_ashrrev_i32_e32 v0, 5, v0
	s_cselect_b32 s15, 0xfffff300, s14
	s_mov_b32 s14, 0x18991000
	v_ashrrev_i32_e32 v137, 31, v136
	v_and_b32_e32 v0, 0xffffff00, v0
	s_cselect_b32 s14, s14, 0x19991000
	v_add_u32_e32 v145, s15, v0
	v_lshlrev_b64 v[132:133], 10, v[136:137]
	v_lshlrev_b64 v[130:131], 11, v[136:137]
	v_or_b32_e32 v0, s16, v142
	s_mov_b64 s[44:45], -1
	s_and_b64 vcc, exec, s[46:47]
	s_barrier
	s_cbranch_vccz .LBB0_496
	s_and_b64 vcc, exec, s[42:43]
	s_cbranch_vccz .LBB0_493
	s_and_b64 vcc, exec, s[62:63]
	s_cbranch_vccz .LBB0_490
	s_and_b64 vcc, exec, s[60:61]
	s_cbranch_vccz .LBB0_487
	s_and_b64 vcc, exec, s[58:59]
	s_cbranch_vccz .LBB0_484
	v_cmp_gt_u32_e32 vcc, s7, v0
	s_and_saveexec_b64 s[44:45], vcc
	s_cbranch_execz .LBB0_483
	v_mul_f32_e32 v137, 0xbfb8aa3b, v126
	v_exp_f32_e32 v137, v137
	v_mul_f32_e32 v143, 0xbfb8aa3b, v127
	v_exp_f32_e32 v143, v143
	v_mul_f32_e32 v147, 0xbfb8aa3b, v129
	v_add_f32_e32 v137, 1.0, v137
	v_rcp_f32_e32 v146, v137
	v_mul_f32_e32 v137, 0xbfb8aa3b, v128
	v_exp_f32_e32 v137, v137
	v_exp_f32_e32 v149, v147
	v_add_f32_e32 v143, 1.0, v143
	v_rcp_f32_e32 v147, v143
	v_add_f32_e32 v137, 1.0, v137
	v_mul_f32_e32 v143, 0xbfb8aa3b, v122
	v_rcp_f32_e32 v148, v137
	v_add_f32_e32 v137, 1.0, v149
	v_exp_f32_e32 v143, v143
	v_mul_f32_e32 v149, 0xbfb8aa3b, v123
	v_exp_f32_e32 v151, v149
	v_rcp_f32_e32 v149, v137
	v_add_f32_e32 v137, 1.0, v143
	v_mul_f32_e32 v143, 0xbfb8aa3b, v124
	v_rcp_f32_e32 v150, v137
	v_add_f32_e32 v137, 1.0, v151
	v_exp_f32_e32 v143, v143
	v_mul_f32_e32 v151, 0xbfb8aa3b, v125
	v_exp_f32_e32 v153, v151
	v_rcp_f32_e32 v151, v137
	v_add_f32_e32 v137, 1.0, v143
	v_rcp_f32_e32 v152, v137
	v_add_f32_e32 v137, 1.0, v153
	v_lshl_add_u64 v[154:155], s[34:35], 0, v[134:135]
	v_rcp_f32_e32 v153, v137
	v_lshl_add_u64 v[154:155], v[0:1], 2, v[154:155]
	v_add_co_u32_e32 v154, vcc, 0x438d000, v154
	s_nop 1
	v_addc_co_u32_e32 v155, vcc, 0, v155, vcc
	global_store_dwordx4 v[154:155], v[146:149], off
	global_store_dwordx4 v[154:155], v[150:153], off offset:16
